# balanced 4/4/4/4 LDS-DMA issue with the moved A stages placed behind the segment's ds_reads (soffset carried in s101)
# baseline (speedup 1.0000x reference)
; #define PG8_WAIT_V(n) asm volatile("s_waitcnt vmcnt(" #n ")" ::: "memory")
; template <class Epi, bool ALIGN_EPI, bool SP2, class Hook>
; __device__ __forceinline__ void gemm_phase(LAS unsigned char* lds, const Gemm g, const StaticOrder& S, const Epi& E, Acc& acc, const bool fresh, const Hook& H, const int wave_id) {
;     ...
;         if constexpr (SP2 && Epi::NSTORE > 0) {
;             const Src a1 = cA + kstep, a2 = cA + 2 * kstep, b2 = cB + 2 * kstep, a3 = a2 + kstep, b3 = b2 + kstep;
;             if constexpr (Epi::NSTORE == 16) PG8_TRIP_SP2(PG8_WAIT_V(24)); else PG8_TRIP_SP2(PG8_WAIT_V(16));
;             t0 = 2;
.LBB0_382:
	ds_read_b128 v[2:5], v150
	ds_read_b128 v[6:9], v150 offset:1024
	ds_read_b128 v[10:13], v150 offset:2048
	ds_read_b128 v[14:17], v150 offset:3072
	ds_read_b128 v[18:21], v151
	ds_read_b128 v[22:25], v151 offset:1024
	ds_read_b128 v[26:29], v151 offset:2048
	ds_read_b128 v[30:33], v151 offset:3072
	s_or_b32 s9, s68, 0x100
	s_or_b32 s8, s68, 0x180
	s_or_b32 s10, s69, 0x100
	s_or_b32 s11, s68, 0x40080
	s_mov_b32 m0, s45
	ds_read_b128 v[34:37], v149
	ds_read_b128 v[38:41], v149 offset:1024
	ds_read_b128 v[42:45], v149 offset:2048
	ds_read_b128 v[46:49], v149 offset:3072
	ds_read_b128 v[50:53], v149 offset:4096
	ds_read_b128 v[54:57], v149 offset:5120
	ds_read_b128 v[58:61], v149 offset:6144
	ds_read_b128 v[62:65], v149 offset:7168
	buffer_load_dwordx4 v144, s[0:3], s11 offen lds
	s_mov_b32 m0, s46
	s_nop 0
	buffer_load_dwordx4 v146, s[0:3], s11 offen lds
	s_waitcnt vmcnt(24)
	s_waitcnt lgkmcnt(0)
	s_setprio 1
	s_barrier
	v_mfma_f32_16x16x32_bf16 v[86:89], v[10:13], v[50:53], 0
	v_mfma_f32_16x16x32_bf16 v[92:95], v[14:17], v[54:57], v[86:89]
	v_mfma_f32_16x16x32_bf16 v[86:89], v[2:5], v[58:61], 0
	v_mfma_f32_16x16x32_bf16 v[66:69], v[2:5], v[34:37], 0
	v_mfma_f32_16x16x32_bf16 v[70:73], v[10:13], v[34:37], 0
	v_mfma_f32_16x16x32_bf16 v[74:77], v[2:5], v[42:45], 0
	v_mfma_f32_16x16x32_bf16 v[78:81], v[10:13], v[42:45], 0
	v_mfma_f32_16x16x32_bf16 v[82:85], v[2:5], v[50:53], 0
	v_mfma_f32_16x16x32_bf16 v[96:99], v[6:9], v[62:65], v[86:89]
	v_mfma_f32_16x16x32_bf16 v[86:89], v[10:13], v[58:61], 0
	v_mfma_f32_16x16x32_bf16 v[66:69], v[6:9], v[38:41], v[66:69]
	v_mfma_f32_16x16x32_bf16 v[70:73], v[14:17], v[38:41], v[70:73]
	v_mfma_f32_16x16x32_bf16 v[74:77], v[6:9], v[46:49], v[74:77]
	v_mfma_f32_16x16x32_bf16 v[78:81], v[14:17], v[46:49], v[78:81]
	v_mfma_f32_16x16x32_bf16 v[82:85], v[6:9], v[54:57], v[82:85]
	v_mfma_f32_16x16x32_bf16 v[104:107], v[14:17], v[62:65], v[86:89]
	v_mfma_f32_16x16x32_bf16 v[86:89], v[18:21], v[34:37], 0
	v_mfma_f32_16x16x32_bf16 v[34:37], v[26:29], v[34:37], 0
	v_mfma_f32_16x16x32_bf16 v[116:119], v[30:33], v[38:41], v[34:37]
	v_mfma_f32_16x16x32_bf16 v[34:37], v[18:21], v[42:45], 0
	v_mfma_f32_16x16x32_bf16 v[132:135], v[22:25], v[46:49], v[34:37]
	v_mfma_f32_16x16x32_bf16 v[34:37], v[26:29], v[42:45], 0
	v_mfma_f32_16x16x32_bf16 v[108:111], v[22:25], v[38:41], v[86:89]
	v_mfma_f32_16x16x32_bf16 v[40:43], v[30:33], v[46:49], v[34:37]
	v_mfma_f32_16x16x32_bf16 v[34:37], v[18:21], v[50:53], 0
	v_mfma_f32_16x16x32_bf16 v[44:47], v[22:25], v[54:57], v[34:37]
	v_mfma_f32_16x16x32_bf16 v[34:37], v[26:29], v[50:53], 0
	v_mfma_f32_16x16x32_bf16 v[48:51], v[30:33], v[54:57], v[34:37]
	v_mfma_f32_16x16x32_bf16 v[34:37], v[18:21], v[58:61], 0
	v_mfma_f32_16x16x32_bf16 v[52:55], v[22:25], v[62:65], v[34:37]
	v_mfma_f32_16x16x32_bf16 v[34:37], v[26:29], v[58:61], 0
	v_mfma_f32_16x16x32_bf16 v[60:63], v[30:33], v[62:65], v[34:37]
	s_barrier
	s_setprio 0
	s_mov_b32 m0, s92
	s_nop 3
	ds_read_b128 v[34:37], v149 offset:16384
	ds_read_b128 v[56:59], v149 offset:17408
	ds_read_b128 v[86:89], v149 offset:18432
	ds_read_b128 v[100:103], v149 offset:19456
	ds_read_b128 v[112:115], v149 offset:20480
	ds_read_b128 v[120:123], v149 offset:21504
	ds_read_b128 v[124:127], v149 offset:22528
	ds_read_b128 v[128:131], v149 offset:23552
	buffer_load_dwordx4 v145, s[4:7], s10 offen lds
	s_mov_b32 m0, s93
	s_nop 0
	buffer_load_dwordx4 v147, s[4:7], s10 offen lds
	s_or_b32 s10, s69, 0x40100
	s_mov_b32 m0, s94
	s_nop 0
	buffer_load_dwordx4 v145, s[4:7], s10 offen lds
	s_mov_b32 m0, s95
	s_nop 0
	buffer_load_dwordx4 v147, s[4:7], s10 offen lds
	s_mov_b32 s101, s9
	s_waitcnt vmcnt(22)
	s_waitcnt lgkmcnt(0)
	s_setprio 1
	s_barrier
	v_mfma_f32_16x16x32_bf16 v[136:139], v[2:5], v[34:37], 0
	v_mfma_f32_16x16x32_bf16 v[154:157], v[2:5], v[86:89], 0
	v_mfma_f32_16x16x32_bf16 v[162:165], v[2:5], v[112:115], 0
	v_mfma_f32_16x16x32_bf16 v[2:5], v[2:5], v[124:127], 0
	v_mfma_f32_16x16x32_bf16 v[136:139], v[6:9], v[56:59], v[136:139]
	v_mfma_f32_16x16x32_bf16 v[140:143], v[10:13], v[34:37], 0
	v_mfma_f32_16x16x32_bf16 v[154:157], v[6:9], v[100:103], v[154:157]
	v_mfma_f32_16x16x32_bf16 v[158:161], v[10:13], v[86:89], 0
	v_mfma_f32_16x16x32_bf16 v[162:165], v[6:9], v[120:123], v[162:165]
	v_mfma_f32_16x16x32_bf16 v[166:169], v[10:13], v[112:115], 0
	v_mfma_f32_16x16x32_bf16 v[2:5], v[6:9], v[128:131], v[2:5]
	v_mfma_f32_16x16x32_bf16 v[6:9], v[10:13], v[124:127], 0
	v_mfma_f32_16x16x32_bf16 v[140:143], v[14:17], v[56:59], v[140:143]
	v_mfma_f32_16x16x32_bf16 v[158:161], v[14:17], v[100:103], v[158:161]
	v_mfma_f32_16x16x32_bf16 v[166:169], v[14:17], v[120:123], v[166:169]
	v_mfma_f32_16x16x32_bf16 v[170:173], v[14:17], v[128:131], v[6:9]
	v_mfma_f32_16x16x32_bf16 v[6:9], v[18:21], v[34:37], 0
	v_mfma_f32_16x16x32_bf16 v[174:177], v[22:25], v[56:59], v[6:9]
	v_mfma_f32_16x16x32_bf16 v[6:9], v[26:29], v[34:37], 0
	v_mfma_f32_16x16x32_bf16 v[178:181], v[30:33], v[56:59], v[6:9]
	v_mfma_f32_16x16x32_bf16 v[6:9], v[18:21], v[86:89], 0
	v_mfma_f32_16x16x32_bf16 v[182:185], v[22:25], v[100:103], v[6:9]
	v_mfma_f32_16x16x32_bf16 v[6:9], v[26:29], v[86:89], 0
	v_mfma_f32_16x16x32_bf16 v[186:189], v[30:33], v[100:103], v[6:9]
	v_mfma_f32_16x16x32_bf16 v[6:9], v[18:21], v[112:115], 0
	v_mfma_f32_16x16x32_bf16 v[190:193], v[22:25], v[120:123], v[6:9]
	v_mfma_f32_16x16x32_bf16 v[6:9], v[26:29], v[112:115], 0
	v_mfma_f32_16x16x32_bf16 v[212:215], v[30:33], v[120:123], v[6:9]
	v_mfma_f32_16x16x32_bf16 v[6:9], v[18:21], v[124:127], 0
	v_mfma_f32_16x16x32_bf16 v[20:23], v[22:25], v[128:131], v[6:9]
	v_mfma_f32_16x16x32_bf16 v[6:9], v[26:29], v[124:127], 0
	v_mfma_f32_16x16x32_bf16 v[216:219], v[30:33], v[128:131], v[6:9]
	s_barrier
; __device__ __forceinline__ const bf16_t* selA(const Gemm& g, int s) { return sel3(g.A0, g.A1, g.A2, s); }
; __device__ __forceinline__ const bf16_t* selB(const Gemm& g, int s) { return sel3(g.B0, g.B1, g.B2, s); }
; __device__ __forceinline__ Src make_src(const bf16_t* p, size_t off) { Src s_; s_.r = __builtin_amdgcn_make_buffer_rsrc((void*)p, (short)0, 0x7fffffff, 0x00020000); s_.o = (unsigned)off; return s_; }
; #define PG8_WAIT_V(n) asm volatile("s_waitcnt vmcnt(" #n ")" ::: "memory")
; template <class Epi, bool ALIGN_EPI, bool SP2, class Hook>
; __device__ __forceinline__ void gemm_phase(LAS unsigned char* lds, const Gemm g, const StaticOrder& S, const Epi& E, Acc& acc, const bool fresh, const Hook& H, const int wave_id) {
;     ...
;     for (;;) {
;         const bool has_next = S.next(ui + 1, nxt);
;         const Src nA = has_next ? make_src(selA(g, nxt.seg), (size_t)nxt.pm * tstepA) : cA, nB = has_next ? make_src(selB(g, nxt.seg), (size_t)nxt.pn * tstep) : cB;
;         for (int t = t0; t < nt; t += 2) {
;             const bool last = (t == nt - 2);
;             const Src a1 = cA + (size_t)(t + 1) * kstep;
;             const Src a2 = last ? nA : cA + (size_t)(t + 2) * kstep, b2 = last ? nB : cB + (size_t)(t + 2) * kstep;
;     ...
;         if constexpr (SP2 && Epi::NSTORE > 0) {
;             const Src a1 = cA + kstep, a2 = cA + 2 * kstep, b2 = cB + 2 * kstep, a3 = a2 + kstep, b3 = b2 + kstep;
;             if constexpr (Epi::NSTORE == 16) PG8_TRIP_SP2(PG8_WAIT_V(24)); else PG8_TRIP_SP2(PG8_WAIT_V(16));
;             t0 = 2;
	s_setprio 0
	s_nop 4
	ds_read_b128 v[6:9], v152
	ds_read_b128 v[24:27], v152 offset:1024
	ds_read_b128 v[228:231], v152 offset:2048
	ds_read_b128 v[232:235], v152 offset:3072
	ds_read_b128 v[236:239], v153
	ds_read_b128 v[240:243], v153 offset:1024
	ds_read_b128 v[244:247], v153 offset:2048
	ds_read_b128 v[150:153], v153 offset:3072
	s_or_b32 s9, s68, 0x40100
	s_mov_b32 m0, s37
	ds_read_b128 v[10:13], v149 offset:32768
	ds_read_b128 v[14:17], v149 offset:33792
	ds_read_b128 v[32:35], v149 offset:34816
	ds_read_b128 v[194:197], v149 offset:35840
	ds_read_b128 v[208:211], v149 offset:36864
	ds_read_b128 v[200:203], v149 offset:37888
	ds_read_b128 v[204:207], v149 offset:38912
	ds_read_b128 v[220:223], v149 offset:39936
	s_mov_b32 m0, s44
	s_nop 0
	buffer_load_dwordx4 v144, s[0:3], s101 offen lds
	s_mov_b32 m0, s36
	s_nop 0
	buffer_load_dwordx4 v146, s[0:3], s101 offen lds
	s_mov_b32 m0, s37
	s_nop 0
	buffer_load_dwordx4 v144, s[0:3], s9 offen lds
	s_mov_b32 m0, s38
	s_nop 0
	buffer_load_dwordx4 v146, s[0:3], s9 offen lds
	s_waitcnt vmcnt(8)
	s_waitcnt lgkmcnt(0)
	s_setprio 1
	s_barrier
	v_mfma_f32_16x16x32_bf16 v[28:31], v[6:9], v[10:13], v[66:69]
	v_mfma_f32_16x16x32_bf16 v[120:123], v[24:27], v[14:17], v[28:31]
	v_mfma_f32_16x16x32_bf16 v[28:31], v[228:231], v[10:13], v[70:73]
	v_mfma_f32_16x16x32_bf16 v[112:115], v[232:235], v[14:17], v[28:31]
	v_mfma_f32_16x16x32_bf16 v[28:31], v[6:9], v[32:35], v[74:77]
	v_mfma_f32_16x16x32_bf16 v[100:103], v[24:27], v[194:197], v[28:31]
	v_mfma_f32_16x16x32_bf16 v[28:31], v[228:231], v[32:35], v[78:81]
	v_mfma_f32_16x16x32_bf16 v[88:91], v[232:235], v[194:197], v[28:31]
	v_mfma_f32_16x16x32_bf16 v[28:31], v[6:9], v[208:211], v[82:85]
	v_mfma_f32_16x16x32_bf16 v[68:71], v[24:27], v[200:203], v[28:31]
	v_mfma_f32_16x16x32_bf16 v[28:31], v[228:231], v[208:211], v[92:95]
	v_mfma_f32_16x16x32_bf16 v[56:59], v[232:235], v[200:203], v[28:31]
	v_mfma_f32_16x16x32_bf16 v[28:31], v[6:9], v[204:207], v[96:99]
	v_mfma_f32_16x16x32_bf16 v[36:39], v[24:27], v[220:223], v[28:31]
	v_mfma_f32_16x16x32_bf16 v[28:31], v[228:231], v[204:207], v[104:107]
	v_mfma_f32_16x16x32_bf16 v[28:31], v[232:235], v[220:223], v[28:31]
	v_mfma_f32_16x16x32_bf16 v[64:67], v[236:239], v[10:13], v[108:111]
	v_mfma_f32_16x16x32_bf16 v[10:13], v[244:247], v[10:13], v[116:119]
	v_mfma_f32_16x16x32_bf16 v[124:127], v[150:153], v[14:17], v[10:13]
	v_mfma_f32_16x16x32_bf16 v[10:13], v[236:239], v[32:35], v[132:135]
	v_mfma_f32_16x16x32_bf16 v[116:119], v[240:243], v[194:197], v[10:13]
	v_mfma_f32_16x16x32_bf16 v[10:13], v[244:247], v[32:35], v[40:43]
	v_mfma_f32_16x16x32_bf16 v[108:111], v[150:153], v[194:197], v[10:13]
	v_mfma_f32_16x16x32_bf16 v[10:13], v[236:239], v[208:211], v[44:47]
	v_mfma_f32_16x16x32_bf16 v[92:95], v[240:243], v[200:203], v[10:13]
	v_mfma_f32_16x16x32_bf16 v[10:13], v[244:247], v[208:211], v[48:51]
	v_mfma_f32_16x16x32_bf16 v[80:83], v[150:153], v[200:203], v[10:13]
	v_mfma_f32_16x16x32_bf16 v[10:13], v[236:239], v[204:207], v[52:55]
	v_mfma_f32_16x16x32_bf16 v[128:131], v[240:243], v[14:17], v[64:67]
	v_mfma_f32_16x16x32_bf16 v[64:67], v[240:243], v[220:223], v[10:13]
	v_mfma_f32_16x16x32_bf16 v[10:13], v[244:247], v[204:207], v[60:63]
	v_mfma_f32_16x16x32_bf16 v[48:51], v[150:153], v[220:223], v[10:13]
	s_barrier
	s_setprio 0
	s_mov_b32 m0, s39
	s_or_b32 s9, s69, 0x180
	ds_read_b128 v[44:47], v149 offset:49152
	ds_read_b128 v[52:55], v149 offset:50176
	ds_read_b128 v[76:79], v149 offset:51200
	ds_read_b128 v[132:135], v149 offset:52224
	ds_read_b128 v[194:197], v149 offset:53248
	ds_read_b128 v[200:203], v149 offset:54272
	ds_read_b128 v[204:207], v149 offset:55296
	ds_read_b128 v[208:211], v149 offset:56320
	buffer_load_dwordx4 v145, s[4:7], s9 offen lds
	s_mov_b32 m0, s40
	s_nop 0
	buffer_load_dwordx4 v147, s[4:7], s9 offen lds
	s_or_b32 s9, s69, 0x40180
	s_mov_b32 m0, s43
	s_nop 0
	buffer_load_dwordx4 v145, s[4:7], s9 offen lds
	s_mov_b32 m0, s42
	s_nop 0
	buffer_load_dwordx4 v147, s[4:7], s9 offen lds
	s_waitcnt vmcnt(6)
	s_waitcnt lgkmcnt(0)
	s_setprio 1
	s_barrier
	v_mfma_f32_16x16x32_bf16 v[10:13], v[6:9], v[44:47], v[136:139]
	v_mfma_f32_16x16x32_bf16 v[72:75], v[24:27], v[52:55], v[10:13]
	v_mfma_f32_16x16x32_bf16 v[10:13], v[228:231], v[44:47], v[140:143]
	v_mfma_f32_16x16x32_bf16 v[60:63], v[232:235], v[52:55], v[10:13]
	v_mfma_f32_16x16x32_bf16 v[10:13], v[6:9], v[76:79], v[154:157]
	v_mfma_f32_16x16x32_bf16 v[40:43], v[24:27], v[132:135], v[10:13]
	v_mfma_f32_16x16x32_bf16 v[10:13], v[228:231], v[76:79], v[158:161]
	v_mfma_f32_16x16x32_bf16 v[32:35], v[232:235], v[132:135], v[10:13]
	v_mfma_f32_16x16x32_bf16 v[10:13], v[6:9], v[194:197], v[162:165]
	v_mfma_f32_16x16x32_bf16 v[16:19], v[24:27], v[200:203], v[10:13]
	v_mfma_f32_16x16x32_bf16 v[10:13], v[228:231], v[194:197], v[166:169]
	v_mfma_f32_16x16x32_bf16 v[2:5], v[6:9], v[204:207], v[2:5]
	v_mfma_f32_16x16x32_bf16 v[12:15], v[232:235], v[200:203], v[10:13]
	v_mfma_f32_16x16x32_bf16 v[8:11], v[24:27], v[208:211], v[2:5]
	v_mfma_f32_16x16x32_bf16 v[2:5], v[228:231], v[204:207], v[170:173]
	v_mfma_f32_16x16x32_bf16 v[4:7], v[232:235], v[208:211], v[2:5]
	v_mfma_f32_16x16x32_bf16 v[24:27], v[236:239], v[44:47], v[174:177]
	v_mfma_f32_16x16x32_bf16 v[96:99], v[240:243], v[52:55], v[24:27]
	v_mfma_f32_16x16x32_bf16 v[24:27], v[244:247], v[44:47], v[178:181]
	v_mfma_f32_16x16x32_bf16 v[104:107], v[150:153], v[52:55], v[24:27]
	v_mfma_f32_16x16x32_bf16 v[24:27], v[236:239], v[76:79], v[182:185]
	v_mfma_f32_16x16x32_bf16 v[84:87], v[240:243], v[132:135], v[24:27]
	v_mfma_f32_16x16x32_bf16 v[24:27], v[244:247], v[76:79], v[186:189]
	v_mfma_f32_16x16x32_bf16 v[76:79], v[150:153], v[132:135], v[24:27]
	v_mfma_f32_16x16x32_bf16 v[24:27], v[236:239], v[194:197], v[190:193]
	v_mfma_f32_16x16x32_bf16 v[52:55], v[240:243], v[200:203], v[24:27]
	v_mfma_f32_16x16x32_bf16 v[24:27], v[244:247], v[194:197], v[212:215]
	v_mfma_f32_16x16x32_bf16 v[20:23], v[236:239], v[204:207], v[20:23]
	v_mfma_f32_16x16x32_bf16 v[44:47], v[150:153], v[200:203], v[24:27]
	v_mfma_f32_16x16x32_bf16 v[24:27], v[240:243], v[208:211], v[20:23]
	v_mfma_f32_16x16x32_bf16 v[20:23], v[244:247], v[204:207], v[216:219]
	v_mfma_f32_16x16x32_bf16 v[20:23], v[150:153], v[208:211], v[20:23]
	s_barrier
	s_setprio 0
	s_mov_b64 s[8:9], 0
	v_mov_b64_e32 v[234:235], v[198:199]
	v_mov_b64_e32 v[236:237], v[226:227]
	v_mov_b32_e32 v198, v0
	v_mov_b32_e32 v226, v225
	v_mov_b64_e32 v[244:245], 0x100
	v_mov_b64_e32 v[246:247], 0xff

; #define PG8_WAIT_V(n) asm volatile("s_waitcnt vmcnt(" #n ")" ::: "memory")
; template <class Epi, bool ALIGN_EPI, bool SP2, class Hook>
; __device__ __forceinline__ void gemm_phase(LAS unsigned char* lds, const Gemm g, const StaticOrder& S, const Epi& E, Acc& acc, const bool fresh, const Hook& H, const int wave_id) {
;     ...
;         for (int t = t0; t < nt; t += 2) {
;             const bool last = (t == nt - 2);
;             const Src a1 = cA + (size_t)(t + 1) * kstep;
;             const Src a2 = last ? nA : cA + (size_t)(t + 2) * kstep, b2 = last ? nB : cB + (size_t)(t + 2) * kstep;
;             const Src a3 = a2 + kstep, b3 = b2 + kstep;
;             if (last && has_next) H(nxt);
;             if constexpr (SP2) {
;             PG8_TRIP_SP2(PG8_WAIT_V(8));
.LBB0_391:
	s_add_i32 s100, s56, 0xfffc0000
	v_add_u32_e32 v150, 0x10000, v148
	v_add_u32_e32 v151, 0x14000, v148
	ds_read_b128 v[132:135], v150
	ds_read_b128 v[136:139], v150 offset:1024
	ds_read_b128 v[140:143], v150 offset:2048
	ds_read_b128 v[152:155], v150 offset:3072
	ds_read_b128 v[156:159], v151
	ds_read_b128 v[160:163], v151 offset:1024
	ds_read_b128 v[164:167], v151 offset:2048
	ds_read_b128 v[168:171], v151 offset:3072
	s_add_i32 s12, s56, 0xfffc0080
	s_cmp_eq_u32 s29, 12
	s_cselect_b32 s60, s68, s12
	s_cselect_b32 s13, s5, s77
	s_cselect_b32 s12, s4, s76
	s_cselect_b32 s15, s7, s55
	s_cselect_b32 s14, s6, s54
	s_cselect_b32 s58, s69, s57
	s_cselect_b32 s16, s0, s8
	s_cselect_b32 s17, s1, s9
	s_cselect_b32 s18, s2, s10
	s_cselect_b32 s19, s3, s11
	s_or_b32 s59, s60, 0x80
	s_mov_b32 m0, s45
	ds_read_b128 v[172:175], v149
	ds_read_b128 v[176:179], v149 offset:1024
	ds_read_b128 v[180:183], v149 offset:2048
	ds_read_b128 v[184:187], v149 offset:3072
	ds_read_b128 v[188:191], v149 offset:4096
	ds_read_b128 v[212:215], v149 offset:5120
	ds_read_b128 v[216:219], v149 offset:6144
	ds_read_b128 v[228:231], v149 offset:7168
	s_mov_b32 m0, s41
	s_nop 0
	buffer_load_dwordx4 v144, s[8:11], s100 offen lds
	s_mov_b32 m0, s33
	s_nop 0
	buffer_load_dwordx4 v146, s[8:11], s100 offen lds
	s_mov_b32 m0, s45
	s_nop 0
	buffer_load_dwordx4 v144, s[8:11], s56 offen lds
	s_mov_b32 m0, s46
	s_nop 0
	buffer_load_dwordx4 v146, s[8:11], s56 offen lds
	s_waitcnt vmcnt(8)
	s_waitcnt lgkmcnt(0)
	s_setprio 1
	s_barrier
	v_mfma_f32_16x16x32_bf16 v[120:123], v[132:135], v[172:175], v[120:123]
	v_mfma_f32_16x16x32_bf16 v[112:115], v[140:143], v[172:175], v[112:115]
	v_mfma_f32_16x16x32_bf16 v[100:103], v[132:135], v[180:183], v[100:103]
	v_mfma_f32_16x16x32_bf16 v[88:91], v[140:143], v[180:183], v[88:91]
	v_mfma_f32_16x16x32_bf16 v[68:71], v[132:135], v[188:191], v[68:71]
	v_mfma_f32_16x16x32_bf16 v[56:59], v[140:143], v[188:191], v[56:59]
	v_mfma_f32_16x16x32_bf16 v[36:39], v[132:135], v[216:219], v[36:39]
	v_mfma_f32_16x16x32_bf16 v[28:31], v[140:143], v[216:219], v[28:31]
	v_mfma_f32_16x16x32_bf16 v[120:123], v[136:139], v[176:179], v[120:123]
	v_mfma_f32_16x16x32_bf16 v[112:115], v[152:155], v[176:179], v[112:115]
	v_mfma_f32_16x16x32_bf16 v[100:103], v[136:139], v[184:187], v[100:103]
	v_mfma_f32_16x16x32_bf16 v[88:91], v[152:155], v[184:187], v[88:91]
	v_mfma_f32_16x16x32_bf16 v[68:71], v[136:139], v[212:215], v[68:71]
	v_mfma_f32_16x16x32_bf16 v[56:59], v[152:155], v[212:215], v[56:59]
	v_mfma_f32_16x16x32_bf16 v[36:39], v[136:139], v[228:231], v[36:39]
	v_mfma_f32_16x16x32_bf16 v[28:31], v[152:155], v[228:231], v[28:31]
	v_mfma_f32_16x16x32_bf16 v[128:131], v[156:159], v[172:175], v[128:131]
	v_mfma_f32_16x16x32_bf16 v[124:127], v[164:167], v[172:175], v[124:127]
	v_mfma_f32_16x16x32_bf16 v[116:119], v[156:159], v[180:183], v[116:119]
	v_mfma_f32_16x16x32_bf16 v[108:111], v[164:167], v[180:183], v[108:111]
	v_mfma_f32_16x16x32_bf16 v[92:95], v[156:159], v[188:191], v[92:95]
	v_mfma_f32_16x16x32_bf16 v[80:83], v[164:167], v[188:191], v[80:83]
	v_mfma_f32_16x16x32_bf16 v[64:67], v[156:159], v[216:219], v[64:67]
	v_mfma_f32_16x16x32_bf16 v[48:51], v[164:167], v[216:219], v[48:51]
	v_mfma_f32_16x16x32_bf16 v[128:131], v[160:163], v[176:179], v[128:131]
	v_mfma_f32_16x16x32_bf16 v[124:127], v[168:171], v[176:179], v[124:127]
	v_mfma_f32_16x16x32_bf16 v[116:119], v[160:163], v[184:187], v[116:119]
	v_mfma_f32_16x16x32_bf16 v[108:111], v[168:171], v[184:187], v[108:111]
	v_mfma_f32_16x16x32_bf16 v[92:95], v[160:163], v[212:215], v[92:95]
	v_mfma_f32_16x16x32_bf16 v[80:83], v[168:171], v[212:215], v[80:83]
	v_mfma_f32_16x16x32_bf16 v[64:67], v[160:163], v[228:231], v[64:67]
	v_mfma_f32_16x16x32_bf16 v[48:51], v[168:171], v[228:231], v[48:51]
	s_barrier
	s_setprio 0
	s_mov_b32 m0, s92
	ds_read_b128 v[172:175], v149 offset:16384
	ds_read_b128 v[176:179], v149 offset:17408
	ds_read_b128 v[180:183], v149 offset:18432
	ds_read_b128 v[184:187], v149 offset:19456
	ds_read_b128 v[188:191], v149 offset:20480
	ds_read_b128 v[212:215], v149 offset:21504
	ds_read_b128 v[216:219], v149 offset:22528
	ds_read_b128 v[228:231], v149 offset:23552
	buffer_load_dwordx4 v145, s[12:15], s58 offen lds
	s_mov_b32 m0, s93
	s_add_i32 s61, s58, 0x40000
	buffer_load_dwordx4 v147, s[12:15], s58 offen lds
	s_mov_b32 m0, s94
	s_nop 0
	buffer_load_dwordx4 v145, s[12:15], s61 offen lds
	s_mov_b32 m0, s95
	s_nop 0
	buffer_load_dwordx4 v147, s[12:15], s61 offen lds
	s_mov_b32 s101, s60
	s_waitcnt vmcnt(6)
	s_waitcnt lgkmcnt(0)
	s_setprio 1
	s_barrier
; #define PG8_WAIT_V(n) asm volatile("s_waitcnt vmcnt(" #n ")" ::: "memory")
; template <class Epi, bool ALIGN_EPI, bool SP2, class Hook>
; __device__ __forceinline__ void gemm_phase(LAS unsigned char* lds, const Gemm g, const StaticOrder& S, const Epi& E, Acc& acc, const bool fresh, const Hook& H, const int wave_id) {
;     ...
;         for (int t = t0; t < nt; t += 2) {
;             const bool last = (t == nt - 2);
;             const Src a1 = cA + (size_t)(t + 1) * kstep;
;             const Src a2 = last ? nA : cA + (size_t)(t + 2) * kstep, b2 = last ? nB : cB + (size_t)(t + 2) * kstep;
;             const Src a3 = a2 + kstep, b3 = b2 + kstep;
;             if (last && has_next) H(nxt);
;             if constexpr (SP2) {
;             PG8_TRIP_SP2(PG8_WAIT_V(8));
	v_mfma_f32_16x16x32_bf16 v[72:75], v[132:135], v[172:175], v[72:75]
	v_mfma_f32_16x16x32_bf16 v[60:63], v[140:143], v[172:175], v[60:63]
	v_mfma_f32_16x16x32_bf16 v[40:43], v[132:135], v[180:183], v[40:43]
	v_mfma_f32_16x16x32_bf16 v[32:35], v[140:143], v[180:183], v[32:35]
	v_mfma_f32_16x16x32_bf16 v[16:19], v[132:135], v[188:191], v[16:19]
	v_mfma_f32_16x16x32_bf16 v[12:15], v[140:143], v[188:191], v[12:15]
	v_mfma_f32_16x16x32_bf16 v[8:11], v[132:135], v[216:219], v[8:11]
	v_mfma_f32_16x16x32_bf16 v[2:5], v[140:143], v[216:219], v[4:7]
	v_mfma_f32_16x16x32_bf16 v[72:75], v[136:139], v[176:179], v[72:75]
	v_mfma_f32_16x16x32_bf16 v[60:63], v[152:155], v[176:179], v[60:63]
	v_mfma_f32_16x16x32_bf16 v[40:43], v[136:139], v[184:187], v[40:43]
	v_mfma_f32_16x16x32_bf16 v[32:35], v[152:155], v[184:187], v[32:35]
	v_mfma_f32_16x16x32_bf16 v[16:19], v[136:139], v[212:215], v[16:19]
	v_mfma_f32_16x16x32_bf16 v[12:15], v[152:155], v[212:215], v[12:15]
	v_mfma_f32_16x16x32_bf16 v[8:11], v[136:139], v[228:231], v[8:11]
	v_mfma_f32_16x16x32_bf16 v[2:5], v[152:155], v[228:231], v[2:5]
	v_mfma_f32_16x16x32_bf16 v[96:99], v[156:159], v[172:175], v[96:99]
	v_mfma_f32_16x16x32_bf16 v[104:107], v[164:167], v[172:175], v[104:107]
	v_mfma_f32_16x16x32_bf16 v[84:87], v[156:159], v[180:183], v[84:87]
	v_mfma_f32_16x16x32_bf16 v[76:79], v[164:167], v[180:183], v[76:79]
	v_mfma_f32_16x16x32_bf16 v[52:55], v[156:159], v[188:191], v[52:55]
	v_mfma_f32_16x16x32_bf16 v[44:47], v[164:167], v[188:191], v[44:47]
	v_mfma_f32_16x16x32_bf16 v[24:27], v[156:159], v[216:219], v[24:27]
	v_mfma_f32_16x16x32_bf16 v[20:23], v[164:167], v[216:219], v[20:23]
	v_mfma_f32_16x16x32_bf16 v[96:99], v[160:163], v[176:179], v[96:99]
	v_mfma_f32_16x16x32_bf16 v[104:107], v[168:171], v[176:179], v[104:107]
	v_mfma_f32_16x16x32_bf16 v[84:87], v[160:163], v[184:187], v[84:87]
	v_mfma_f32_16x16x32_bf16 v[76:79], v[168:171], v[184:187], v[76:79]
	v_mfma_f32_16x16x32_bf16 v[52:55], v[160:163], v[212:215], v[52:55]
	v_mfma_f32_16x16x32_bf16 v[44:47], v[168:171], v[212:215], v[44:47]
	v_mfma_f32_16x16x32_bf16 v[24:27], v[160:163], v[228:231], v[24:27]
	v_mfma_f32_16x16x32_bf16 v[20:23], v[168:171], v[228:231], v[20:23]
	s_barrier
	s_setprio 0
	v_add_u32_e32 v152, 0x18000, v148
	v_add_u32_e32 v153, 0x1c000, v148
	ds_read_b128 v[132:135], v152
	ds_read_b128 v[136:139], v152 offset:1024
	ds_read_b128 v[140:143], v152 offset:2048
	ds_read_b128 v[154:157], v152 offset:3072
	ds_read_b128 v[158:161], v153
	ds_read_b128 v[162:165], v153 offset:1024
	ds_read_b128 v[166:169], v153 offset:2048
	ds_read_b128 v[170:173], v153 offset:3072
	s_add_i32 s60, s60, 0x40000
	s_mov_b32 m0, s37
	ds_read_b128 v[174:177], v149 offset:32768
	ds_read_b128 v[178:181], v149 offset:33792
	ds_read_b128 v[182:185], v149 offset:34816
	ds_read_b128 v[186:189], v149 offset:35840
	ds_read_b128 v[190:193], v149 offset:36864
	ds_read_b128 v[212:215], v149 offset:37888
	ds_read_b128 v[216:219], v149 offset:38912
	ds_read_b128 v[228:231], v149 offset:39936
	s_mov_b32 m0, s44
	s_nop 0
	buffer_load_dwordx4 v144, s[16:19], s101 offen lds
	s_mov_b32 m0, s36
	s_nop 0
	buffer_load_dwordx4 v146, s[16:19], s101 offen lds
	s_mov_b32 m0, s37
	s_nop 0
	buffer_load_dwordx4 v144, s[16:19], s60 offen lds
	s_mov_b32 m0, s38
	s_nop 0
	buffer_load_dwordx4 v146, s[16:19], s60 offen lds
	s_waitcnt vmcnt(8)
	s_waitcnt lgkmcnt(0)
	s_setprio 1
	s_barrier
	v_mfma_f32_16x16x32_bf16 v[120:123], v[132:135], v[174:177], v[120:123]
	v_mfma_f32_16x16x32_bf16 v[112:115], v[140:143], v[174:177], v[112:115]
	v_mfma_f32_16x16x32_bf16 v[100:103], v[132:135], v[182:185], v[100:103]
	v_mfma_f32_16x16x32_bf16 v[88:91], v[140:143], v[182:185], v[88:91]
	v_mfma_f32_16x16x32_bf16 v[68:71], v[132:135], v[190:193], v[68:71]
	v_mfma_f32_16x16x32_bf16 v[56:59], v[140:143], v[190:193], v[56:59]
	v_mfma_f32_16x16x32_bf16 v[36:39], v[132:135], v[216:219], v[36:39]
	v_mfma_f32_16x16x32_bf16 v[28:31], v[140:143], v[216:219], v[28:31]
	v_mfma_f32_16x16x32_bf16 v[120:123], v[136:139], v[178:181], v[120:123]
	v_mfma_f32_16x16x32_bf16 v[112:115], v[154:157], v[178:181], v[112:115]
	v_mfma_f32_16x16x32_bf16 v[100:103], v[136:139], v[186:189], v[100:103]
	v_mfma_f32_16x16x32_bf16 v[88:91], v[154:157], v[186:189], v[88:91]
	v_mfma_f32_16x16x32_bf16 v[68:71], v[136:139], v[212:215], v[68:71]
	v_mfma_f32_16x16x32_bf16 v[56:59], v[154:157], v[212:215], v[56:59]
	v_mfma_f32_16x16x32_bf16 v[36:39], v[136:139], v[228:231], v[36:39]
	v_mfma_f32_16x16x32_bf16 v[28:31], v[154:157], v[228:231], v[28:31]
	v_mfma_f32_16x16x32_bf16 v[128:131], v[158:161], v[174:177], v[128:131]
	v_mfma_f32_16x16x32_bf16 v[124:127], v[166:169], v[174:177], v[124:127]
	v_mfma_f32_16x16x32_bf16 v[116:119], v[158:161], v[182:185], v[116:119]
	v_mfma_f32_16x16x32_bf16 v[108:111], v[166:169], v[182:185], v[108:111]
	v_mfma_f32_16x16x32_bf16 v[92:95], v[158:161], v[190:193], v[92:95]
	v_mfma_f32_16x16x32_bf16 v[80:83], v[166:169], v[190:193], v[80:83]
	v_mfma_f32_16x16x32_bf16 v[64:67], v[158:161], v[216:219], v[64:67]
	v_mfma_f32_16x16x32_bf16 v[48:51], v[166:169], v[216:219], v[48:51]
	v_mfma_f32_16x16x32_bf16 v[128:131], v[162:165], v[178:181], v[128:131]
	v_mfma_f32_16x16x32_bf16 v[124:127], v[170:173], v[178:181], v[124:127]
	v_mfma_f32_16x16x32_bf16 v[116:119], v[162:165], v[186:189], v[116:119]
	v_mfma_f32_16x16x32_bf16 v[108:111], v[170:173], v[186:189], v[108:111]
	v_mfma_f32_16x16x32_bf16 v[92:95], v[162:165], v[212:215], v[92:95]
	v_mfma_f32_16x16x32_bf16 v[80:83], v[170:173], v[212:215], v[80:83]
	v_mfma_f32_16x16x32_bf16 v[64:67], v[162:165], v[228:231], v[64:67]
	v_mfma_f32_16x16x32_bf16 v[48:51], v[170:173], v[228:231], v[48:51]
	s_barrier
; #define PG8_STAGE(bufoff, gbase, voff) do { const Src _g = (gbase); _Pragma("unroll") for (int _i = 0; _i < 2; ++_i) \
;         __builtin_amdgcn_raw_ptr_buffer_load_lds(_g.r, (LAS unsigned*)(lds + (bufoff) + ldsw + _i * 8192), 16, (voff)[_i], _g.o, 0, 0); } while (0)
; #define PG8_WAIT_V(n) asm volatile("s_waitcnt vmcnt(" #n ")" ::: "memory")
; template <class Epi, bool ALIGN_EPI, bool SP2, class Hook>
; __device__ __forceinline__ void gemm_phase(LAS unsigned char* lds, const Gemm g, const StaticOrder& S, const Epi& E, Acc& acc, const bool fresh, const Hook& H, const int wave_id) {
;     ...
;         for (int t = t0; t < nt; t += 2) {
;             const bool last = (t == nt - 2);
;             const Src a1 = cA + (size_t)(t + 1) * kstep;
;             const Src a2 = last ? nA : cA + (size_t)(t + 2) * kstep, b2 = last ? nB : cB + (size_t)(t + 2) * kstep;
;             const Src a3 = a2 + kstep, b3 = b2 + kstep;
;             if (last && has_next) H(nxt);
;             if constexpr (SP2) {
;             PG8_TRIP_SP2(PG8_WAIT_V(8));
;             } else {
;             PG8_LDB(B0, 0, 0); PG8_SCHED; PG8_LDA(At, 0, 0); PG8_STAGE(PG8_SA(1, 1), a1 + hstepA, voffA);
;             PG8_WAIT_L(8); PG8_BAR; PG8_WAIT_L(0); PG8_MMA(0, 0, At, B0); PG8_BAR; PG8_SCHED;
;             PG8_LDB(B1, 0, 1); PG8_STAGE(PG8_SB(0, 0), b2, voffB);
;             PG8_BAR; PG8_WAIT_L(0); PG8_MMA(0, 1, At, B1); PG8_BAR;
;             PG8_LDA(At, 0, 1); PG8_STAGE(PG8_SA(0, 0), a2, voffA);
;             PG8_BAR; PG8_WAIT_L(0); PG8_MMA(1, 0, At, B0); PG8_BAR; PG8_SCHED;
;             PG8_STAGE(PG8_SB(0, 1), b2 + hstep, voffB);
;             PG8_WAIT_V(6); PG8_BAR; PG8_MMA(1, 1, At, B1); PG8_BAR;
;             PG8_LDB(B0, 1, 0); PG8_SCHED; PG8_LDA(At, 1, 0); PG8_STAGE(PG8_SA(0, 1), a2 + hstepA, voffA);
;             PG8_WAIT_L(8); PG8_BAR; PG8_WAIT_L(0); PG8_MMA(0, 0, At, B0); PG8_BAR; PG8_SCHED;
;             PG8_LDB(B1, 1, 1); PG8_STAGE(PG8_SB(1, 0), b3, voffB);
;             PG8_BAR; PG8_WAIT_L(0); PG8_MMA(0, 1, At, B1); PG8_BAR;
;             PG8_LDA(At, 1, 1); PG8_STAGE(PG8_SA(1, 0), a3, voffA);
;             PG8_BAR; PG8_WAIT_L(0); PG8_MMA(1, 0, At, B0); PG8_BAR; PG8_SCHED;
;             PG8_STAGE(PG8_SB(1, 1), b3 + hstep, voffB);
;             PG8_WAIT_V(6); PG8_BAR; PG8_MMA(1, 1, At, B1); PG8_BAR;
;             }
;         }
;         if constexpr (ALIGN_EPI) { if (wr == 0) PG8_BAR; }
	s_setprio 0
	s_mov_b32 m0, s39
	s_or_b32 s60, s58, 0x80
	ds_read_b128 v[174:177], v149 offset:49152
	ds_read_b128 v[178:181], v149 offset:50176
	ds_read_b128 v[182:185], v149 offset:51200
	ds_read_b128 v[186:189], v149 offset:52224
	ds_read_b128 v[190:193], v149 offset:53248
	ds_read_b128 v[212:215], v149 offset:54272
	ds_read_b128 v[216:219], v149 offset:55296
	ds_read_b128 v[228:231], v149 offset:56320
	buffer_load_dwordx4 v145, s[12:15], s60 offen lds
	s_mov_b32 m0, s40
	s_add_i32 s58, s58, 0x40080
	buffer_load_dwordx4 v147, s[12:15], s60 offen lds
	s_mov_b32 m0, s43
	s_nop 0
	buffer_load_dwordx4 v145, s[12:15], s58 offen lds
	s_mov_b32 m0, s42
	s_nop 0
	buffer_load_dwordx4 v147, s[12:15], s58 offen lds
	s_waitcnt vmcnt(6)
	s_waitcnt lgkmcnt(0)
	s_setprio 1
	s_barrier
	v_mfma_f32_16x16x32_bf16 v[72:75], v[132:135], v[174:177], v[72:75]
	v_mfma_f32_16x16x32_bf16 v[60:63], v[140:143], v[174:177], v[60:63]
	v_mfma_f32_16x16x32_bf16 v[40:43], v[132:135], v[182:185], v[40:43]
	v_mfma_f32_16x16x32_bf16 v[32:35], v[140:143], v[182:185], v[32:35]
	v_mfma_f32_16x16x32_bf16 v[16:19], v[132:135], v[190:193], v[16:19]
	v_mfma_f32_16x16x32_bf16 v[12:15], v[140:143], v[190:193], v[12:15]
	v_mfma_f32_16x16x32_bf16 v[6:9], v[132:135], v[216:219], v[8:11]
	v_mfma_f32_16x16x32_bf16 v[2:5], v[140:143], v[216:219], v[2:5]
	v_mfma_f32_16x16x32_bf16 v[72:75], v[136:139], v[178:181], v[72:75]
	v_mfma_f32_16x16x32_bf16 v[60:63], v[154:157], v[178:181], v[60:63]
	v_mfma_f32_16x16x32_bf16 v[40:43], v[136:139], v[186:189], v[40:43]
	v_mfma_f32_16x16x32_bf16 v[32:35], v[154:157], v[186:189], v[32:35]
	v_mfma_f32_16x16x32_bf16 v[16:19], v[136:139], v[212:215], v[16:19]
	v_mfma_f32_16x16x32_bf16 v[12:15], v[154:157], v[212:215], v[12:15]
	v_mfma_f32_16x16x32_bf16 v[8:11], v[136:139], v[228:231], v[6:9]
	v_mfma_f32_16x16x32_bf16 v[4:7], v[154:157], v[228:231], v[2:5]
	v_mfma_f32_16x16x32_bf16 v[96:99], v[158:161], v[174:177], v[96:99]
	v_mfma_f32_16x16x32_bf16 v[104:107], v[166:169], v[174:177], v[104:107]
	v_mfma_f32_16x16x32_bf16 v[84:87], v[158:161], v[182:185], v[84:87]
	v_mfma_f32_16x16x32_bf16 v[76:79], v[166:169], v[182:185], v[76:79]
	v_mfma_f32_16x16x32_bf16 v[52:55], v[158:161], v[190:193], v[52:55]
	v_mfma_f32_16x16x32_bf16 v[44:47], v[166:169], v[190:193], v[44:47]
	v_mfma_f32_16x16x32_bf16 v[24:27], v[158:161], v[216:219], v[24:27]
	v_mfma_f32_16x16x32_bf16 v[20:23], v[166:169], v[216:219], v[20:23]
	v_mfma_f32_16x16x32_bf16 v[96:99], v[162:165], v[178:181], v[96:99]
	v_mfma_f32_16x16x32_bf16 v[104:107], v[170:173], v[178:181], v[104:107]
	v_mfma_f32_16x16x32_bf16 v[84:87], v[162:165], v[186:189], v[84:87]
	v_mfma_f32_16x16x32_bf16 v[76:79], v[170:173], v[186:189], v[76:79]
	v_mfma_f32_16x16x32_bf16 v[52:55], v[162:165], v[212:215], v[52:55]
	v_mfma_f32_16x16x32_bf16 v[44:47], v[170:173], v[212:215], v[44:47]
	v_mfma_f32_16x16x32_bf16 v[24:27], v[162:165], v[228:231], v[24:27]
	v_mfma_f32_16x16x32_bf16 v[20:23], v[170:173], v[228:231], v[20:23]
	s_barrier
	s_setprio 0
	s_add_i32 s29, s29, 2
	s_addk_i32 s56, 0x100
	s_addk_i32 s57, 0x100
	s_cmp_gt_u32 s29, 13
	s_cbranch_scc0 .LBB0_391
	s_mov_b32 m0, s41
	s_nop 0
	buffer_load_dwordx4 v144, s[16:19], s59 offen lds
	s_mov_b32 m0, s33
	s_nop 0
	buffer_load_dwordx4 v146, s[16:19], s59 offen lds
	v_readlane_b32 s8, v251, 45
	v_readlane_b32 s9, v251, 46
	s_and_b64 vcc, exec, s[8:9]
	s_cbranch_vccz .LBB0_394
	s_barrier

; #define PG8_WAIT_V(n) asm volatile("s_waitcnt vmcnt(" #n ")" ::: "memory")
; template <class Epi, bool ALIGN_EPI, bool SP2, class Hook>
; __device__ __forceinline__ void gemm_phase(LAS unsigned char* lds, const Gemm g, const StaticOrder& S, const Epi& E, Acc& acc, const bool fresh, const Hook& H, const int wave_id) {
;     ...
;         for (int t = t0; t < nt; t += 2) {
;             const bool last = (t == nt - 2);
;             const Src a1 = cA + (size_t)(t + 1) * kstep;
;             const Src a2 = last ? nA : cA + (size_t)(t + 2) * kstep, b2 = last ? nB : cB + (size_t)(t + 2) * kstep;
;             const Src a3 = a2 + kstep, b3 = b2 + kstep;
;             if (last && has_next) H(nxt);
;             if constexpr (SP2) {
;             PG8_TRIP_SP2(PG8_WAIT_V(8));
.LBB0_903:
	s_add_i32 s100, s55, 0xfffe0000
	v_add_u32_e32 v70, 0x10000, v216
	v_add_u32_e32 v118, 0x14000, v216
	ds_read_b128 v[34:37], v70
	ds_read_b128 v[46:49], v70 offset:1024
	ds_read_b128 v[58:61], v70 offset:2048
	ds_read_b128 v[70:73], v70 offset:3072
	ds_read_b128 v[82:85], v118
	ds_read_b128 v[94:97], v118 offset:1024
	ds_read_b128 v[106:109], v118 offset:2048
	ds_read_b128 v[118:121], v118 offset:3072
	s_add_i32 s12, s55, 0xfffe0080
	s_cmp_eq_u32 s57, 4
	s_cselect_b32 s60, s53, s12
	s_cselect_b32 s13, s29, s77
	s_cselect_b32 s12, s28, s76
	s_cselect_b32 s15, s31, s35
	s_cselect_b32 s14, s30, s34
	s_cselect_b32 s58, s54, s56
	s_cselect_b32 s16, s2, s8
	s_cselect_b32 s17, s3, s9
	s_cselect_b32 s18, s26, s10
	s_cselect_b32 s19, s27, s11
	s_or_b32 s59, s60, 0x80
	s_mov_b32 m0, s45
	ds_read_b128 v[130:133], v217
	ds_read_b128 v[142:145], v217 offset:1024
	ds_read_b128 v[154:157], v217 offset:2048
	ds_read_b128 v[166:169], v217 offset:3072
	ds_read_b128 v[174:177], v217 offset:4096
	ds_read_b128 v[182:185], v217 offset:5120
	ds_read_b128 v[186:189], v217 offset:6144
	ds_read_b128 v[190:193], v217 offset:7168
	s_mov_b32 m0, s41
	s_nop 0
	buffer_load_dwordx4 v0, s[8:11], s100 offen lds
	s_mov_b32 m0, s33
	s_nop 0
	buffer_load_dwordx4 v214, s[8:11], s100 offen lds
	s_mov_b32 m0, s45
	s_nop 0
	buffer_load_dwordx4 v0, s[8:11], s55 offen lds
	s_mov_b32 m0, s46
	s_nop 0
	buffer_load_dwordx4 v214, s[8:11], s55 offen lds
	s_waitcnt vmcnt(8)
	s_waitcnt lgkmcnt(0)
	s_setprio 1
	s_barrier
	v_mfma_f32_16x16x32_bf16 v[178:181], v[34:37], v[130:133], v[178:181]
	v_mfma_f32_16x16x32_bf16 v[170:173], v[58:61], v[130:133], v[170:173]
	v_mfma_f32_16x16x32_bf16 v[150:153], v[34:37], v[154:157], v[150:153]
	v_mfma_f32_16x16x32_bf16 v[146:149], v[58:61], v[154:157], v[146:149]
	v_mfma_f32_16x16x32_bf16 v[126:129], v[34:37], v[174:177], v[126:129]
	v_mfma_f32_16x16x32_bf16 v[122:125], v[58:61], v[174:177], v[122:125]
	v_mfma_f32_16x16x32_bf16 v[102:105], v[34:37], v[186:189], v[102:105]
	v_mfma_f32_16x16x32_bf16 v[98:101], v[58:61], v[186:189], v[98:101]
	v_mfma_f32_16x16x32_bf16 v[178:181], v[46:49], v[142:145], v[178:181]
	v_mfma_f32_16x16x32_bf16 v[170:173], v[70:73], v[142:145], v[170:173]
	v_mfma_f32_16x16x32_bf16 v[150:153], v[46:49], v[166:169], v[150:153]
	v_mfma_f32_16x16x32_bf16 v[146:149], v[70:73], v[166:169], v[146:149]
	v_mfma_f32_16x16x32_bf16 v[126:129], v[46:49], v[182:185], v[126:129]
	v_mfma_f32_16x16x32_bf16 v[122:125], v[70:73], v[182:185], v[122:125]
	v_mfma_f32_16x16x32_bf16 v[102:105], v[46:49], v[190:193], v[102:105]
	v_mfma_f32_16x16x32_bf16 v[98:101], v[70:73], v[190:193], v[98:101]
	v_mfma_f32_16x16x32_bf16 v[162:165], v[82:85], v[130:133], v[162:165]
	v_mfma_f32_16x16x32_bf16 v[138:141], v[82:85], v[154:157], v[138:141]
	v_mfma_f32_16x16x32_bf16 v[134:137], v[106:109], v[154:157], v[134:137]
	v_mfma_f32_16x16x32_bf16 v[114:117], v[82:85], v[174:177], v[114:117]
	v_mfma_f32_16x16x32_bf16 v[110:113], v[106:109], v[174:177], v[110:113]
	v_mfma_f32_16x16x32_bf16 v[90:93], v[82:85], v[186:189], v[90:93]
	v_mfma_f32_16x16x32_bf16 v[86:89], v[106:109], v[186:189], v[86:89]
	v_mfma_f32_16x16x32_bf16 v[162:165], v[94:97], v[142:145], v[162:165]
	v_mfma_f32_16x16x32_bf16 v[130:133], v[106:109], v[130:133], v[158:161]
	v_mfma_f32_16x16x32_bf16 v[138:141], v[94:97], v[166:169], v[138:141]
	v_mfma_f32_16x16x32_bf16 v[134:137], v[118:121], v[166:169], v[134:137]
	v_mfma_f32_16x16x32_bf16 v[114:117], v[94:97], v[182:185], v[114:117]
	v_mfma_f32_16x16x32_bf16 v[110:113], v[118:121], v[182:185], v[110:113]
	v_mfma_f32_16x16x32_bf16 v[90:93], v[94:97], v[190:193], v[90:93]
	v_mfma_f32_16x16x32_bf16 v[86:89], v[118:121], v[190:193], v[86:89]
	v_mfma_f32_16x16x32_bf16 v[130:133], v[118:121], v[142:145], v[130:133]
	s_barrier
	s_setprio 0
	s_mov_b32 m0, s92
	ds_read_b128 v[142:145], v217 offset:16384
	ds_read_b128 v[154:157], v217 offset:17408
	ds_read_b128 v[158:161], v217 offset:18432
	ds_read_b128 v[166:169], v217 offset:19456
	ds_read_b128 v[174:177], v217 offset:20480
	ds_read_b128 v[182:185], v217 offset:21504
	ds_read_b128 v[186:189], v217 offset:22528
	ds_read_b128 v[190:193], v217 offset:23552
	buffer_load_dwordx4 v199, s[12:15], s58 offen lds
	s_mov_b32 m0, s93
	s_add_i32 s61, s58, 0x20000
	buffer_load_dwordx4 v215, s[12:15], s58 offen lds
	s_mov_b32 m0, s94
	s_nop 0
	buffer_load_dwordx4 v199, s[12:15], s61 offen lds
	s_mov_b32 m0, s95
	s_nop 0
	buffer_load_dwordx4 v215, s[12:15], s61 offen lds
	s_mov_b32 s101, s60
	s_waitcnt vmcnt(6)
	s_waitcnt lgkmcnt(0)
	s_setprio 1
	s_barrier
; #define PG8_WAIT_V(n) asm volatile("s_waitcnt vmcnt(" #n ")" ::: "memory")
; template <class Epi, bool ALIGN_EPI, bool SP2, class Hook>
; __device__ __forceinline__ void gemm_phase(LAS unsigned char* lds, const Gemm g, const StaticOrder& S, const Epi& E, Acc& acc, const bool fresh, const Hook& H, const int wave_id) {
;     ...
;         for (int t = t0; t < nt; t += 2) {
;             const bool last = (t == nt - 2);
;             const Src a1 = cA + (size_t)(t + 1) * kstep;
;             const Src a2 = last ? nA : cA + (size_t)(t + 2) * kstep, b2 = last ? nB : cB + (size_t)(t + 2) * kstep;
;             const Src a3 = a2 + kstep, b3 = b2 + kstep;
;             if (last && has_next) H(nxt);
;             if constexpr (SP2) {
;             PG8_TRIP_SP2(PG8_WAIT_V(8));
	v_mfma_f32_16x16x32_bf16 v[78:81], v[34:37], v[142:145], v[78:81]
	v_mfma_f32_16x16x32_bf16 v[74:77], v[58:61], v[142:145], v[74:77]
	v_mfma_f32_16x16x32_bf16 v[54:57], v[34:37], v[158:161], v[54:57]
	v_mfma_f32_16x16x32_bf16 v[50:53], v[58:61], v[158:161], v[50:53]
	v_mfma_f32_16x16x32_bf16 v[30:33], v[34:37], v[174:177], v[30:33]
	v_mfma_f32_16x16x32_bf16 v[26:29], v[58:61], v[174:177], v[26:29]
	v_mfma_f32_16x16x32_bf16 v[14:17], v[34:37], v[186:189], v[14:17]
	v_mfma_f32_16x16x32_bf16 v[10:13], v[58:61], v[186:189], v[10:13]
	v_mfma_f32_16x16x32_bf16 v[78:81], v[46:49], v[154:157], v[78:81]
	v_mfma_f32_16x16x32_bf16 v[74:77], v[70:73], v[154:157], v[74:77]
	v_mfma_f32_16x16x32_bf16 v[54:57], v[46:49], v[166:169], v[54:57]
	v_mfma_f32_16x16x32_bf16 v[50:53], v[70:73], v[166:169], v[50:53]
	v_mfma_f32_16x16x32_bf16 v[30:33], v[46:49], v[182:185], v[30:33]
	v_mfma_f32_16x16x32_bf16 v[26:29], v[70:73], v[182:185], v[26:29]
	v_mfma_f32_16x16x32_bf16 v[14:17], v[46:49], v[190:193], v[14:17]
	v_mfma_f32_16x16x32_bf16 v[10:13], v[70:73], v[190:193], v[10:13]
	v_mfma_f32_16x16x32_bf16 v[42:45], v[82:85], v[158:161], v[42:45]
	v_mfma_f32_16x16x32_bf16 v[38:41], v[106:109], v[158:161], v[38:41]
	v_mfma_f32_16x16x32_bf16 v[22:25], v[82:85], v[174:177], v[22:25]
	v_mfma_f32_16x16x32_bf16 v[18:21], v[106:109], v[174:177], v[18:21]
	v_mfma_f32_16x16x32_bf16 v[6:9], v[82:85], v[186:189], v[6:9]
	v_mfma_f32_16x16x32_bf16 v[2:5], v[106:109], v[186:189], v[2:5]
	v_mfma_f32_16x16x32_bf16 v[34:37], v[82:85], v[142:145], v[66:69]
	v_mfma_f32_16x16x32_bf16 v[46:49], v[106:109], v[142:145], v[62:65]
	v_mfma_f32_16x16x32_bf16 v[42:45], v[94:97], v[166:169], v[42:45]
	v_mfma_f32_16x16x32_bf16 v[38:41], v[118:121], v[166:169], v[38:41]
	v_mfma_f32_16x16x32_bf16 v[22:25], v[94:97], v[182:185], v[22:25]
	v_mfma_f32_16x16x32_bf16 v[18:21], v[118:121], v[182:185], v[18:21]
	v_mfma_f32_16x16x32_bf16 v[6:9], v[94:97], v[190:193], v[6:9]
	v_mfma_f32_16x16x32_bf16 v[2:5], v[118:121], v[190:193], v[2:5]
	v_mfma_f32_16x16x32_bf16 v[34:37], v[94:97], v[154:157], v[34:37]
	v_mfma_f32_16x16x32_bf16 v[46:49], v[118:121], v[154:157], v[46:49]
	s_barrier
	s_setprio 0
	v_add_u32_e32 v70, 0x18000, v216
	v_add_u32_e32 v118, 0x1c000, v216
	ds_read_b128 v[58:61], v70
	ds_read_b128 v[62:65], v70 offset:1024
	ds_read_b128 v[66:69], v70 offset:2048
	ds_read_b128 v[70:73], v70 offset:3072
	ds_read_b128 v[82:85], v118
	ds_read_b128 v[94:97], v118 offset:1024
	ds_read_b128 v[106:109], v118 offset:2048
	ds_read_b128 v[118:121], v118 offset:3072
	s_add_i32 s60, s60, 0x20000
	s_mov_b32 m0, s37
	ds_read_b128 v[142:145], v217 offset:32768
	ds_read_b128 v[154:157], v217 offset:33792
	ds_read_b128 v[166:169], v217 offset:34816
	ds_read_b128 v[174:177], v217 offset:35840
	ds_read_b128 v[182:185], v217 offset:36864
	ds_read_b128 v[186:189], v217 offset:37888
	ds_read_b128 v[190:193], v217 offset:38912
	ds_read_b128 v[194:197], v217 offset:39936
	s_mov_b32 m0, s44
	s_nop 0
	buffer_load_dwordx4 v0, s[16:19], s101 offen lds
	s_mov_b32 m0, s36
	s_nop 0
	buffer_load_dwordx4 v214, s[16:19], s101 offen lds
	s_mov_b32 m0, s37
	s_nop 0
	buffer_load_dwordx4 v0, s[16:19], s60 offen lds
	s_mov_b32 m0, s38
	s_nop 0
	buffer_load_dwordx4 v214, s[16:19], s60 offen lds
	s_waitcnt vmcnt(8)
	s_waitcnt lgkmcnt(0)
	s_setprio 1
	s_barrier
	v_mfma_f32_16x16x32_bf16 v[158:161], v[58:61], v[142:145], v[178:181]
	v_mfma_f32_16x16x32_bf16 v[178:181], v[62:65], v[154:157], v[158:161]
	v_mfma_f32_16x16x32_bf16 v[158:161], v[66:69], v[142:145], v[170:173]
	v_mfma_f32_16x16x32_bf16 v[150:153], v[58:61], v[166:169], v[150:153]
	v_mfma_f32_16x16x32_bf16 v[146:149], v[66:69], v[166:169], v[146:149]
	v_mfma_f32_16x16x32_bf16 v[126:129], v[58:61], v[182:185], v[126:129]
	v_mfma_f32_16x16x32_bf16 v[122:125], v[66:69], v[182:185], v[122:125]
	v_mfma_f32_16x16x32_bf16 v[102:105], v[58:61], v[190:193], v[102:105]
	v_mfma_f32_16x16x32_bf16 v[98:101], v[66:69], v[190:193], v[98:101]
	v_mfma_f32_16x16x32_bf16 v[170:173], v[70:73], v[154:157], v[158:161]
	v_mfma_f32_16x16x32_bf16 v[150:153], v[62:65], v[174:177], v[150:153]
	v_mfma_f32_16x16x32_bf16 v[146:149], v[70:73], v[174:177], v[146:149]
	v_mfma_f32_16x16x32_bf16 v[126:129], v[62:65], v[186:189], v[126:129]
	v_mfma_f32_16x16x32_bf16 v[122:125], v[70:73], v[186:189], v[122:125]
	v_mfma_f32_16x16x32_bf16 v[102:105], v[62:65], v[194:197], v[102:105]
	v_mfma_f32_16x16x32_bf16 v[98:101], v[70:73], v[194:197], v[98:101]
	v_mfma_f32_16x16x32_bf16 v[158:161], v[82:85], v[142:145], v[162:165]
	v_mfma_f32_16x16x32_bf16 v[130:133], v[106:109], v[142:145], v[130:133]
	v_mfma_f32_16x16x32_bf16 v[162:165], v[94:97], v[154:157], v[158:161]
	v_mfma_f32_16x16x32_bf16 v[158:161], v[118:121], v[154:157], v[130:133]
	v_mfma_f32_16x16x32_bf16 v[130:133], v[82:85], v[166:169], v[138:141]
	v_mfma_f32_16x16x32_bf16 v[138:141], v[94:97], v[174:177], v[130:133]
	v_mfma_f32_16x16x32_bf16 v[130:133], v[106:109], v[166:169], v[134:137]
	v_mfma_f32_16x16x32_bf16 v[114:117], v[82:85], v[182:185], v[114:117]
	v_mfma_f32_16x16x32_bf16 v[110:113], v[106:109], v[182:185], v[110:113]
	v_mfma_f32_16x16x32_bf16 v[90:93], v[82:85], v[190:193], v[90:93]
	v_mfma_f32_16x16x32_bf16 v[86:89], v[106:109], v[190:193], v[86:89]
	v_mfma_f32_16x16x32_bf16 v[134:137], v[118:121], v[174:177], v[130:133]
	v_mfma_f32_16x16x32_bf16 v[114:117], v[94:97], v[186:189], v[114:117]
	v_mfma_f32_16x16x32_bf16 v[110:113], v[118:121], v[186:189], v[110:113]
	v_mfma_f32_16x16x32_bf16 v[90:93], v[94:97], v[194:197], v[90:93]
	v_mfma_f32_16x16x32_bf16 v[86:89], v[118:121], v[194:197], v[86:89]
	s_barrier
; #define PG8_STAGE(bufoff, gbase, voff) do { const Src _g = (gbase); _Pragma("unroll") for (int _i = 0; _i < 2; ++_i) \
;         __builtin_amdgcn_raw_ptr_buffer_load_lds(_g.r, (LAS unsigned*)(lds + (bufoff) + ldsw + _i * 8192), 16, (voff)[_i], _g.o, 0, 0); } while (0)
; #define PG8_WAIT_V(n) asm volatile("s_waitcnt vmcnt(" #n ")" ::: "memory")
; template <class Epi, bool ALIGN_EPI, bool SP2, class Hook>
; __device__ __forceinline__ void gemm_phase(LAS unsigned char* lds, const Gemm g, const StaticOrder& S, const Epi& E, Acc& acc, const bool fresh, const Hook& H, const int wave_id) {
;     ...
;         for (int t = t0; t < nt; t += 2) {
;             const bool last = (t == nt - 2);
;             const Src a1 = cA + (size_t)(t + 1) * kstep;
;             const Src a2 = last ? nA : cA + (size_t)(t + 2) * kstep, b2 = last ? nB : cB + (size_t)(t + 2) * kstep;
;             const Src a3 = a2 + kstep, b3 = b2 + kstep;
;             if (last && has_next) H(nxt);
;             if constexpr (SP2) {
;             PG8_TRIP_SP2(PG8_WAIT_V(8));
;             } else {
;             PG8_LDB(B0, 0, 0); PG8_SCHED; PG8_LDA(At, 0, 0); PG8_STAGE(PG8_SA(1, 1), a1 + hstepA, voffA);
;             PG8_WAIT_L(8); PG8_BAR; PG8_WAIT_L(0); PG8_MMA(0, 0, At, B0); PG8_BAR; PG8_SCHED;
;             PG8_LDB(B1, 0, 1); PG8_STAGE(PG8_SB(0, 0), b2, voffB);
;             PG8_BAR; PG8_WAIT_L(0); PG8_MMA(0, 1, At, B1); PG8_BAR;
;             PG8_LDA(At, 0, 1); PG8_STAGE(PG8_SA(0, 0), a2, voffA);
;             PG8_BAR; PG8_WAIT_L(0); PG8_MMA(1, 0, At, B0); PG8_BAR; PG8_SCHED;
;             PG8_STAGE(PG8_SB(0, 1), b2 + hstep, voffB);
;             PG8_WAIT_V(6); PG8_BAR; PG8_MMA(1, 1, At, B1); PG8_BAR;
;             PG8_LDB(B0, 1, 0); PG8_SCHED; PG8_LDA(At, 1, 0); PG8_STAGE(PG8_SA(0, 1), a2 + hstepA, voffA);
;             PG8_WAIT_L(8); PG8_BAR; PG8_WAIT_L(0); PG8_MMA(0, 0, At, B0); PG8_BAR; PG8_SCHED;
;             PG8_LDB(B1, 1, 1); PG8_STAGE(PG8_SB(1, 0), b3, voffB);
;             PG8_BAR; PG8_WAIT_L(0); PG8_MMA(0, 1, At, B1); PG8_BAR;
;             PG8_LDA(At, 1, 1); PG8_STAGE(PG8_SA(1, 0), a3, voffA);
;             PG8_BAR; PG8_WAIT_L(0); PG8_MMA(1, 0, At, B0); PG8_BAR; PG8_SCHED;
;             PG8_STAGE(PG8_SB(1, 1), b3 + hstep, voffB);
;             PG8_WAIT_V(6); PG8_BAR; PG8_MMA(1, 1, At, B1); PG8_BAR;
;             }
;         }
;         if constexpr (ALIGN_EPI) { if (wr == 0) PG8_BAR; }
	s_setprio 0
	s_mov_b32 m0, s39
	s_or_b32 s60, s58, 0x80
	ds_read_b128 v[130:133], v217 offset:49152
	ds_read_b128 v[142:145], v217 offset:50176
	ds_read_b128 v[154:157], v217 offset:51200
	ds_read_b128 v[166:169], v217 offset:52224
	ds_read_b128 v[174:177], v217 offset:53248
	ds_read_b128 v[182:185], v217 offset:54272
	ds_read_b128 v[186:189], v217 offset:55296
	ds_read_b128 v[190:193], v217 offset:56320
	buffer_load_dwordx4 v199, s[12:15], s60 offen lds
	s_mov_b32 m0, s40
	s_add_i32 s58, s58, 0x20080
	buffer_load_dwordx4 v215, s[12:15], s60 offen lds
	s_mov_b32 m0, s43
	s_nop 0
	buffer_load_dwordx4 v199, s[12:15], s58 offen lds
	s_mov_b32 m0, s42
	s_nop 0
	buffer_load_dwordx4 v215, s[12:15], s58 offen lds
	s_waitcnt vmcnt(6)
	s_waitcnt lgkmcnt(0)
	s_setprio 1
	s_barrier
	v_mfma_f32_16x16x32_bf16 v[78:81], v[58:61], v[130:133], v[78:81]
	v_mfma_f32_16x16x32_bf16 v[74:77], v[66:69], v[130:133], v[74:77]
	v_mfma_f32_16x16x32_bf16 v[54:57], v[58:61], v[154:157], v[54:57]
	v_mfma_f32_16x16x32_bf16 v[50:53], v[66:69], v[154:157], v[50:53]
	v_mfma_f32_16x16x32_bf16 v[30:33], v[58:61], v[174:177], v[30:33]
	v_mfma_f32_16x16x32_bf16 v[26:29], v[66:69], v[174:177], v[26:29]
	v_mfma_f32_16x16x32_bf16 v[14:17], v[58:61], v[186:189], v[14:17]
	v_mfma_f32_16x16x32_bf16 v[10:13], v[66:69], v[186:189], v[10:13]
	v_mfma_f32_16x16x32_bf16 v[78:81], v[62:65], v[142:145], v[78:81]
	v_mfma_f32_16x16x32_bf16 v[74:77], v[70:73], v[142:145], v[74:77]
	v_mfma_f32_16x16x32_bf16 v[54:57], v[62:65], v[166:169], v[54:57]
	v_mfma_f32_16x16x32_bf16 v[50:53], v[70:73], v[166:169], v[50:53]
	v_mfma_f32_16x16x32_bf16 v[30:33], v[62:65], v[182:185], v[30:33]
	v_mfma_f32_16x16x32_bf16 v[26:29], v[70:73], v[182:185], v[26:29]
	v_mfma_f32_16x16x32_bf16 v[14:17], v[62:65], v[190:193], v[14:17]
	v_mfma_f32_16x16x32_bf16 v[10:13], v[70:73], v[190:193], v[10:13]
	v_mfma_f32_16x16x32_bf16 v[34:37], v[82:85], v[130:133], v[34:37]
	v_mfma_f32_16x16x32_bf16 v[66:69], v[94:97], v[142:145], v[34:37]
	v_mfma_f32_16x16x32_bf16 v[34:37], v[106:109], v[130:133], v[46:49]
	v_mfma_f32_16x16x32_bf16 v[62:65], v[118:121], v[142:145], v[34:37]
	v_mfma_f32_16x16x32_bf16 v[34:37], v[82:85], v[154:157], v[42:45]
	v_mfma_f32_16x16x32_bf16 v[42:45], v[94:97], v[166:169], v[34:37]
	v_mfma_f32_16x16x32_bf16 v[34:37], v[106:109], v[154:157], v[38:41]
	v_mfma_f32_16x16x32_bf16 v[22:25], v[82:85], v[174:177], v[22:25]
	v_mfma_f32_16x16x32_bf16 v[18:21], v[106:109], v[174:177], v[18:21]
	v_mfma_f32_16x16x32_bf16 v[6:9], v[82:85], v[186:189], v[6:9]
	v_mfma_f32_16x16x32_bf16 v[2:5], v[106:109], v[186:189], v[2:5]
	v_mfma_f32_16x16x32_bf16 v[38:41], v[118:121], v[166:169], v[34:37]
	v_mfma_f32_16x16x32_bf16 v[22:25], v[94:97], v[182:185], v[22:25]
	v_mfma_f32_16x16x32_bf16 v[18:21], v[118:121], v[182:185], v[18:21]
	v_mfma_f32_16x16x32_bf16 v[6:9], v[94:97], v[190:193], v[6:9]
	v_mfma_f32_16x16x32_bf16 v[2:5], v[118:121], v[190:193], v[2:5]
	s_barrier
	s_setprio 0
	s_add_i32 s57, s57, 2
	s_addk_i32 s55, 0x100
	s_addk_i32 s56, 0x100
	s_cmp_gt_u32 s57, 5
	s_cbranch_scc0 .LBB0_903
	s_mov_b32 m0, s41
	s_nop 0
	buffer_load_dwordx4 v0, s[16:19], s59 offen lds
	s_mov_b32 m0, s33
	s_nop 0
	buffer_load_dwordx4 v214, s[16:19], s59 offen lds
	v_readlane_b32 s8, v251, 45
	v_readlane_b32 s9, v251, 46
	s_and_b64 vcc, exec, s[8:9]
	s_cbranch_vccz .LBB0_906
	s_barrier

; #define PG8_WAIT_V(n) asm volatile("s_waitcnt vmcnt(" #n ")" ::: "memory")
; template <class Epi, bool ALIGN_EPI, bool SP2, class Hook>
; __device__ __forceinline__ void gemm_phase(LAS unsigned char* lds, const Gemm g, const StaticOrder& S, const Epi& E, Acc& acc, const bool fresh, const Hook& H, const int wave_id) {
;     ...
;         for (int t = t0; t < nt; t += 2) {
;             const bool last = (t == nt - 2);
;             const Src a1 = cA + (size_t)(t + 1) * kstep;
;             const Src a2 = last ? nA : cA + (size_t)(t + 2) * kstep, b2 = last ? nB : cB + (size_t)(t + 2) * kstep;
;             const Src a3 = a2 + kstep, b3 = b2 + kstep;
;             if (last && has_next) H(nxt);
;             if constexpr (SP2) {
;             PG8_TRIP_SP2(PG8_WAIT_V(8));
.LBB0_1235:
	s_add_i32 s100, s2, 0xfffc0000
	v_add_u32_e32 v142, 0x10000, v161
	v_add_u32_e32 v163, 0x14000, v161
	ds_read_b128 v[130:133], v142
	ds_read_b128 v[134:137], v142 offset:1024
	ds_read_b128 v[138:141], v142 offset:2048
	ds_read_b128 v[142:145], v142 offset:3072
	ds_read_b128 v[146:149], v163
	ds_read_b128 v[150:153], v163 offset:1024
	ds_read_b128 v[154:157], v163 offset:2048
	ds_read_b128 v[164:167], v163 offset:3072
	s_add_i32 s16, s2, 0xfffc0080
	s_cmp_eq_u32 s59, 12
	s_cselect_b32 s62, s55, s16
	s_cselect_b32 s17, s31, s9
	s_cselect_b32 s16, s30, s8
	s_cselect_b32 s19, s35, s51
	s_cselect_b32 s18, s34, s50
	s_cselect_b32 s60, s56, s3
	s_cselect_b32 s20, s26, s12
	s_cselect_b32 s21, s27, s13
	s_cselect_b32 s22, s28, s14
	s_cselect_b32 s23, s29, s15
	s_or_b32 s61, s62, 0x80
	s_mov_b32 m0, s45
	ds_read_b128 v[168:171], v162
	ds_read_b128 v[172:175], v162 offset:1024
	ds_read_b128 v[176:179], v162 offset:2048
	ds_read_b128 v[180:183], v162 offset:3072
	ds_read_b128 v[184:187], v162 offset:4096
	ds_read_b128 v[188:191], v162 offset:5120
	ds_read_b128 v[192:195], v162 offset:6144
	ds_read_b128 v[200:203], v162 offset:7168
	s_mov_b32 m0, s41
	s_nop 0
	buffer_load_dwordx4 v0, s[12:15], s100 offen lds
	s_mov_b32 m0, s33
	s_nop 0
	buffer_load_dwordx4 v159, s[12:15], s100 offen lds
	s_mov_b32 m0, s45
	s_nop 0
	buffer_load_dwordx4 v0, s[12:15], s2 offen lds
	s_mov_b32 m0, s46
	s_nop 0
	buffer_load_dwordx4 v159, s[12:15], s2 offen lds
	s_waitcnt vmcnt(8)
	s_waitcnt lgkmcnt(0)
	s_setprio 1
	s_barrier
	v_mfma_f32_16x16x32_bf16 v[126:129], v[130:133], v[168:171], v[126:129]
	v_mfma_f32_16x16x32_bf16 v[122:125], v[138:141], v[168:171], v[122:125]
	v_mfma_f32_16x16x32_bf16 v[110:113], v[130:133], v[176:179], v[110:113]
	v_mfma_f32_16x16x32_bf16 v[106:109], v[138:141], v[176:179], v[106:109]
	v_mfma_f32_16x16x32_bf16 v[94:97], v[130:133], v[184:187], v[94:97]
	v_mfma_f32_16x16x32_bf16 v[90:93], v[138:141], v[184:187], v[90:93]
	v_mfma_f32_16x16x32_bf16 v[78:81], v[130:133], v[192:195], v[78:81]
	v_mfma_f32_16x16x32_bf16 v[74:77], v[138:141], v[192:195], v[74:77]
	v_mfma_f32_16x16x32_bf16 v[126:129], v[134:137], v[172:175], v[126:129]
	v_mfma_f32_16x16x32_bf16 v[122:125], v[142:145], v[172:175], v[122:125]
	v_mfma_f32_16x16x32_bf16 v[110:113], v[134:137], v[180:183], v[110:113]
	v_mfma_f32_16x16x32_bf16 v[106:109], v[142:145], v[180:183], v[106:109]
	v_mfma_f32_16x16x32_bf16 v[94:97], v[134:137], v[188:191], v[94:97]
	v_mfma_f32_16x16x32_bf16 v[90:93], v[142:145], v[188:191], v[90:93]
	v_mfma_f32_16x16x32_bf16 v[78:81], v[134:137], v[200:203], v[78:81]
	v_mfma_f32_16x16x32_bf16 v[74:77], v[142:145], v[200:203], v[74:77]
	v_mfma_f32_16x16x32_bf16 v[118:121], v[146:149], v[168:171], v[118:121]
	v_mfma_f32_16x16x32_bf16 v[114:117], v[154:157], v[168:171], v[114:117]
	v_mfma_f32_16x16x32_bf16 v[102:105], v[146:149], v[176:179], v[102:105]
	v_mfma_f32_16x16x32_bf16 v[98:101], v[154:157], v[176:179], v[98:101]
	v_mfma_f32_16x16x32_bf16 v[86:89], v[146:149], v[184:187], v[86:89]
	v_mfma_f32_16x16x32_bf16 v[82:85], v[154:157], v[184:187], v[82:85]
	v_mfma_f32_16x16x32_bf16 v[70:73], v[146:149], v[192:195], v[70:73]
	v_mfma_f32_16x16x32_bf16 v[66:69], v[154:157], v[192:195], v[66:69]
	v_mfma_f32_16x16x32_bf16 v[118:121], v[150:153], v[172:175], v[118:121]
	v_mfma_f32_16x16x32_bf16 v[114:117], v[164:167], v[172:175], v[114:117]
	v_mfma_f32_16x16x32_bf16 v[102:105], v[150:153], v[180:183], v[102:105]
	v_mfma_f32_16x16x32_bf16 v[98:101], v[164:167], v[180:183], v[98:101]
	v_mfma_f32_16x16x32_bf16 v[86:89], v[150:153], v[188:191], v[86:89]
	v_mfma_f32_16x16x32_bf16 v[82:85], v[164:167], v[188:191], v[82:85]
	v_mfma_f32_16x16x32_bf16 v[70:73], v[150:153], v[200:203], v[70:73]
	v_mfma_f32_16x16x32_bf16 v[66:69], v[164:167], v[200:203], v[66:69]
	s_barrier
	s_setprio 0
	s_mov_b32 m0, s92
	ds_read_b128 v[168:171], v162 offset:16384
	ds_read_b128 v[172:175], v162 offset:17408
	ds_read_b128 v[176:179], v162 offset:18432
	ds_read_b128 v[180:183], v162 offset:19456
	ds_read_b128 v[184:187], v162 offset:20480
	ds_read_b128 v[188:191], v162 offset:21504
	ds_read_b128 v[192:195], v162 offset:22528
	ds_read_b128 v[200:203], v162 offset:23552
	buffer_load_dwordx4 v158, s[16:19], s60 offen lds
	s_mov_b32 m0, s93
	s_add_i32 s63, s60, 0x40000
	buffer_load_dwordx4 v160, s[16:19], s60 offen lds
	s_mov_b32 m0, s94
	s_nop 0
	buffer_load_dwordx4 v158, s[16:19], s63 offen lds
	s_mov_b32 m0, s95
	s_nop 0
	buffer_load_dwordx4 v160, s[16:19], s63 offen lds
	s_mov_b32 s101, s62
	s_waitcnt vmcnt(6)
	s_waitcnt lgkmcnt(0)
	s_setprio 1
	s_barrier
; #define PG8_WAIT_V(n) asm volatile("s_waitcnt vmcnt(" #n ")" ::: "memory")
; template <class Epi, bool ALIGN_EPI, bool SP2, class Hook>
; __device__ __forceinline__ void gemm_phase(LAS unsigned char* lds, const Gemm g, const StaticOrder& S, const Epi& E, Acc& acc, const bool fresh, const Hook& H, const int wave_id) {
;     ...
;         for (int t = t0; t < nt; t += 2) {
;             const bool last = (t == nt - 2);
;             const Src a1 = cA + (size_t)(t + 1) * kstep;
;             const Src a2 = last ? nA : cA + (size_t)(t + 2) * kstep, b2 = last ? nB : cB + (size_t)(t + 2) * kstep;
;             const Src a3 = a2 + kstep, b3 = b2 + kstep;
;             if (last && has_next) H(nxt);
;             if constexpr (SP2) {
;             PG8_TRIP_SP2(PG8_WAIT_V(8));
	v_mfma_f32_16x16x32_bf16 v[62:65], v[130:133], v[168:171], v[62:65]
	v_mfma_f32_16x16x32_bf16 v[58:61], v[138:141], v[168:171], v[58:61]
	v_mfma_f32_16x16x32_bf16 v[46:49], v[130:133], v[176:179], v[46:49]
	v_mfma_f32_16x16x32_bf16 v[42:45], v[138:141], v[176:179], v[42:45]
	v_mfma_f32_16x16x32_bf16 v[30:33], v[130:133], v[184:187], v[30:33]
	v_mfma_f32_16x16x32_bf16 v[26:29], v[138:141], v[184:187], v[26:29]
	v_mfma_f32_16x16x32_bf16 v[14:17], v[130:133], v[192:195], v[14:17]
	v_mfma_f32_16x16x32_bf16 v[10:13], v[138:141], v[192:195], v[10:13]
	v_mfma_f32_16x16x32_bf16 v[62:65], v[134:137], v[172:175], v[62:65]
	v_mfma_f32_16x16x32_bf16 v[58:61], v[142:145], v[172:175], v[58:61]
	v_mfma_f32_16x16x32_bf16 v[46:49], v[134:137], v[180:183], v[46:49]
	v_mfma_f32_16x16x32_bf16 v[42:45], v[142:145], v[180:183], v[42:45]
	v_mfma_f32_16x16x32_bf16 v[30:33], v[134:137], v[188:191], v[30:33]
	v_mfma_f32_16x16x32_bf16 v[26:29], v[142:145], v[188:191], v[26:29]
	v_mfma_f32_16x16x32_bf16 v[14:17], v[134:137], v[200:203], v[14:17]
	v_mfma_f32_16x16x32_bf16 v[10:13], v[142:145], v[200:203], v[10:13]
	v_mfma_f32_16x16x32_bf16 v[54:57], v[146:149], v[168:171], v[54:57]
	v_mfma_f32_16x16x32_bf16 v[50:53], v[154:157], v[168:171], v[50:53]
	v_mfma_f32_16x16x32_bf16 v[38:41], v[146:149], v[176:179], v[38:41]
	v_mfma_f32_16x16x32_bf16 v[34:37], v[154:157], v[176:179], v[34:37]
	v_mfma_f32_16x16x32_bf16 v[22:25], v[146:149], v[184:187], v[22:25]
	v_mfma_f32_16x16x32_bf16 v[18:21], v[154:157], v[184:187], v[18:21]
	v_mfma_f32_16x16x32_bf16 v[6:9], v[146:149], v[192:195], v[6:9]
	v_mfma_f32_16x16x32_bf16 v[2:5], v[154:157], v[192:195], v[2:5]
	v_mfma_f32_16x16x32_bf16 v[54:57], v[150:153], v[172:175], v[54:57]
	v_mfma_f32_16x16x32_bf16 v[50:53], v[164:167], v[172:175], v[50:53]
	v_mfma_f32_16x16x32_bf16 v[38:41], v[150:153], v[180:183], v[38:41]
	v_mfma_f32_16x16x32_bf16 v[34:37], v[164:167], v[180:183], v[34:37]
	v_mfma_f32_16x16x32_bf16 v[22:25], v[150:153], v[188:191], v[22:25]
	v_mfma_f32_16x16x32_bf16 v[18:21], v[164:167], v[188:191], v[18:21]
	v_mfma_f32_16x16x32_bf16 v[6:9], v[150:153], v[200:203], v[6:9]
	v_mfma_f32_16x16x32_bf16 v[2:5], v[164:167], v[200:203], v[2:5]
	s_barrier
	s_setprio 0
	v_add_u32_e32 v142, 0x18000, v161
	v_add_u32_e32 v163, 0x1c000, v161
	ds_read_b128 v[130:133], v142
	ds_read_b128 v[134:137], v142 offset:1024
	ds_read_b128 v[138:141], v142 offset:2048
	ds_read_b128 v[142:145], v142 offset:3072
	ds_read_b128 v[146:149], v163
	ds_read_b128 v[150:153], v163 offset:1024
	ds_read_b128 v[154:157], v163 offset:2048
	ds_read_b128 v[164:167], v163 offset:3072
	s_add_i32 s62, s62, 0x40000
	s_mov_b32 m0, s37
	ds_read_b128 v[168:171], v162 offset:32768
	ds_read_b128 v[172:175], v162 offset:33792
	ds_read_b128 v[176:179], v162 offset:34816
	ds_read_b128 v[180:183], v162 offset:35840
	ds_read_b128 v[184:187], v162 offset:36864
	ds_read_b128 v[188:191], v162 offset:37888
	ds_read_b128 v[192:195], v162 offset:38912
	ds_read_b128 v[200:203], v162 offset:39936
	s_mov_b32 m0, s44
	s_nop 0
	buffer_load_dwordx4 v0, s[20:23], s101 offen lds
	s_mov_b32 m0, s36
	s_nop 0
	buffer_load_dwordx4 v159, s[20:23], s101 offen lds
	s_mov_b32 m0, s37
	s_nop 0
	buffer_load_dwordx4 v0, s[20:23], s62 offen lds
	s_mov_b32 m0, s38
	s_nop 0
	buffer_load_dwordx4 v159, s[20:23], s62 offen lds
	s_waitcnt vmcnt(8)
	s_waitcnt lgkmcnt(0)
	s_setprio 1
	s_barrier
	v_mfma_f32_16x16x32_bf16 v[126:129], v[130:133], v[168:171], v[126:129]
	v_mfma_f32_16x16x32_bf16 v[122:125], v[138:141], v[168:171], v[122:125]
	v_mfma_f32_16x16x32_bf16 v[110:113], v[130:133], v[176:179], v[110:113]
	v_mfma_f32_16x16x32_bf16 v[106:109], v[138:141], v[176:179], v[106:109]
	v_mfma_f32_16x16x32_bf16 v[94:97], v[130:133], v[184:187], v[94:97]
	v_mfma_f32_16x16x32_bf16 v[90:93], v[138:141], v[184:187], v[90:93]
	v_mfma_f32_16x16x32_bf16 v[78:81], v[130:133], v[192:195], v[78:81]
	v_mfma_f32_16x16x32_bf16 v[74:77], v[138:141], v[192:195], v[74:77]
	v_mfma_f32_16x16x32_bf16 v[126:129], v[134:137], v[172:175], v[126:129]
	v_mfma_f32_16x16x32_bf16 v[122:125], v[142:145], v[172:175], v[122:125]
	v_mfma_f32_16x16x32_bf16 v[110:113], v[134:137], v[180:183], v[110:113]
	v_mfma_f32_16x16x32_bf16 v[106:109], v[142:145], v[180:183], v[106:109]
	v_mfma_f32_16x16x32_bf16 v[94:97], v[134:137], v[188:191], v[94:97]
	v_mfma_f32_16x16x32_bf16 v[90:93], v[142:145], v[188:191], v[90:93]
	v_mfma_f32_16x16x32_bf16 v[78:81], v[134:137], v[200:203], v[78:81]
	v_mfma_f32_16x16x32_bf16 v[74:77], v[142:145], v[200:203], v[74:77]
	v_mfma_f32_16x16x32_bf16 v[118:121], v[146:149], v[168:171], v[118:121]
	v_mfma_f32_16x16x32_bf16 v[114:117], v[154:157], v[168:171], v[114:117]
	v_mfma_f32_16x16x32_bf16 v[102:105], v[146:149], v[176:179], v[102:105]
	v_mfma_f32_16x16x32_bf16 v[98:101], v[154:157], v[176:179], v[98:101]
	v_mfma_f32_16x16x32_bf16 v[86:89], v[146:149], v[184:187], v[86:89]
	v_mfma_f32_16x16x32_bf16 v[82:85], v[154:157], v[184:187], v[82:85]
	v_mfma_f32_16x16x32_bf16 v[70:73], v[146:149], v[192:195], v[70:73]
	v_mfma_f32_16x16x32_bf16 v[66:69], v[154:157], v[192:195], v[66:69]
	v_mfma_f32_16x16x32_bf16 v[118:121], v[150:153], v[172:175], v[118:121]
	v_mfma_f32_16x16x32_bf16 v[114:117], v[164:167], v[172:175], v[114:117]
	v_mfma_f32_16x16x32_bf16 v[102:105], v[150:153], v[180:183], v[102:105]
	v_mfma_f32_16x16x32_bf16 v[98:101], v[164:167], v[180:183], v[98:101]
	v_mfma_f32_16x16x32_bf16 v[86:89], v[150:153], v[188:191], v[86:89]
	v_mfma_f32_16x16x32_bf16 v[82:85], v[164:167], v[188:191], v[82:85]
	v_mfma_f32_16x16x32_bf16 v[70:73], v[150:153], v[200:203], v[70:73]
	v_mfma_f32_16x16x32_bf16 v[66:69], v[164:167], v[200:203], v[66:69]
	s_barrier
; #define PG8_STAGE(bufoff, gbase, voff) do { const Src _g = (gbase); _Pragma("unroll") for (int _i = 0; _i < 2; ++_i) \
;         __builtin_amdgcn_raw_ptr_buffer_load_lds(_g.r, (LAS unsigned*)(lds + (bufoff) + ldsw + _i * 8192), 16, (voff)[_i], _g.o, 0, 0); } while (0)
; #define PG8_WAIT_V(n) asm volatile("s_waitcnt vmcnt(" #n ")" ::: "memory")
; template <class Epi, bool ALIGN_EPI, bool SP2, class Hook>
; __device__ __forceinline__ void gemm_phase(LAS unsigned char* lds, const Gemm g, const StaticOrder& S, const Epi& E, Acc& acc, const bool fresh, const Hook& H, const int wave_id) {
;     ...
;         for (int t = t0; t < nt; t += 2) {
;             const bool last = (t == nt - 2);
;             const Src a1 = cA + (size_t)(t + 1) * kstep;
;             const Src a2 = last ? nA : cA + (size_t)(t + 2) * kstep, b2 = last ? nB : cB + (size_t)(t + 2) * kstep;
;             const Src a3 = a2 + kstep, b3 = b2 + kstep;
;             if (last && has_next) H(nxt);
;             if constexpr (SP2) {
;             PG8_TRIP_SP2(PG8_WAIT_V(8));
;             } else {
;             PG8_LDB(B0, 0, 0); PG8_SCHED; PG8_LDA(At, 0, 0); PG8_STAGE(PG8_SA(1, 1), a1 + hstepA, voffA);
;             PG8_WAIT_L(8); PG8_BAR; PG8_WAIT_L(0); PG8_MMA(0, 0, At, B0); PG8_BAR; PG8_SCHED;
;             PG8_LDB(B1, 0, 1); PG8_STAGE(PG8_SB(0, 0), b2, voffB);
;             PG8_BAR; PG8_WAIT_L(0); PG8_MMA(0, 1, At, B1); PG8_BAR;
;             PG8_LDA(At, 0, 1); PG8_STAGE(PG8_SA(0, 0), a2, voffA);
;             PG8_BAR; PG8_WAIT_L(0); PG8_MMA(1, 0, At, B0); PG8_BAR; PG8_SCHED;
;             PG8_STAGE(PG8_SB(0, 1), b2 + hstep, voffB);
;             PG8_WAIT_V(6); PG8_BAR; PG8_MMA(1, 1, At, B1); PG8_BAR;
;             PG8_LDB(B0, 1, 0); PG8_SCHED; PG8_LDA(At, 1, 0); PG8_STAGE(PG8_SA(0, 1), a2 + hstepA, voffA);
;             PG8_WAIT_L(8); PG8_BAR; PG8_WAIT_L(0); PG8_MMA(0, 0, At, B0); PG8_BAR; PG8_SCHED;
;             PG8_LDB(B1, 1, 1); PG8_STAGE(PG8_SB(1, 0), b3, voffB);
;             PG8_BAR; PG8_WAIT_L(0); PG8_MMA(0, 1, At, B1); PG8_BAR;
;             PG8_LDA(At, 1, 1); PG8_STAGE(PG8_SA(1, 0), a3, voffA);
;             PG8_BAR; PG8_WAIT_L(0); PG8_MMA(1, 0, At, B0); PG8_BAR; PG8_SCHED;
;             PG8_STAGE(PG8_SB(1, 1), b3 + hstep, voffB);
;             PG8_WAIT_V(6); PG8_BAR; PG8_MMA(1, 1, At, B1); PG8_BAR;
;             }
;         }
;         if constexpr (ALIGN_EPI) { if (wr == 0) PG8_BAR; }
	s_setprio 0
	s_mov_b32 m0, s39
	s_or_b32 s62, s60, 0x80
	ds_read_b128 v[168:171], v162 offset:49152
	ds_read_b128 v[172:175], v162 offset:50176
	ds_read_b128 v[176:179], v162 offset:51200
	ds_read_b128 v[180:183], v162 offset:52224
	ds_read_b128 v[184:187], v162 offset:53248
	ds_read_b128 v[188:191], v162 offset:54272
	ds_read_b128 v[192:195], v162 offset:55296
	ds_read_b128 v[200:203], v162 offset:56320
	buffer_load_dwordx4 v158, s[16:19], s62 offen lds
	s_mov_b32 m0, s40
	s_add_i32 s60, s60, 0x40080
	buffer_load_dwordx4 v160, s[16:19], s62 offen lds
	s_mov_b32 m0, s43
	s_nop 0
	buffer_load_dwordx4 v158, s[16:19], s60 offen lds
	s_mov_b32 m0, s42
	s_nop 0
	buffer_load_dwordx4 v160, s[16:19], s60 offen lds
	s_waitcnt vmcnt(6)
	s_waitcnt lgkmcnt(0)
	s_setprio 1
	s_barrier
	v_mfma_f32_16x16x32_bf16 v[62:65], v[130:133], v[168:171], v[62:65]
	v_mfma_f32_16x16x32_bf16 v[58:61], v[138:141], v[168:171], v[58:61]
	v_mfma_f32_16x16x32_bf16 v[46:49], v[130:133], v[176:179], v[46:49]
	v_mfma_f32_16x16x32_bf16 v[42:45], v[138:141], v[176:179], v[42:45]
	v_mfma_f32_16x16x32_bf16 v[30:33], v[130:133], v[184:187], v[30:33]
	v_mfma_f32_16x16x32_bf16 v[26:29], v[138:141], v[184:187], v[26:29]
	v_mfma_f32_16x16x32_bf16 v[14:17], v[130:133], v[192:195], v[14:17]
	v_mfma_f32_16x16x32_bf16 v[10:13], v[138:141], v[192:195], v[10:13]
	v_mfma_f32_16x16x32_bf16 v[62:65], v[134:137], v[172:175], v[62:65]
	v_mfma_f32_16x16x32_bf16 v[58:61], v[142:145], v[172:175], v[58:61]
	v_mfma_f32_16x16x32_bf16 v[46:49], v[134:137], v[180:183], v[46:49]
	v_mfma_f32_16x16x32_bf16 v[42:45], v[142:145], v[180:183], v[42:45]
	v_mfma_f32_16x16x32_bf16 v[30:33], v[134:137], v[188:191], v[30:33]
	v_mfma_f32_16x16x32_bf16 v[26:29], v[142:145], v[188:191], v[26:29]
	v_mfma_f32_16x16x32_bf16 v[14:17], v[134:137], v[200:203], v[14:17]
	v_mfma_f32_16x16x32_bf16 v[10:13], v[142:145], v[200:203], v[10:13]
	v_mfma_f32_16x16x32_bf16 v[54:57], v[146:149], v[168:171], v[54:57]
	v_mfma_f32_16x16x32_bf16 v[50:53], v[154:157], v[168:171], v[50:53]
	v_mfma_f32_16x16x32_bf16 v[38:41], v[146:149], v[176:179], v[38:41]
	v_mfma_f32_16x16x32_bf16 v[34:37], v[154:157], v[176:179], v[34:37]
	v_mfma_f32_16x16x32_bf16 v[22:25], v[146:149], v[184:187], v[22:25]
	v_mfma_f32_16x16x32_bf16 v[18:21], v[154:157], v[184:187], v[18:21]
	v_mfma_f32_16x16x32_bf16 v[6:9], v[146:149], v[192:195], v[6:9]
	v_mfma_f32_16x16x32_bf16 v[2:5], v[154:157], v[192:195], v[2:5]
	v_mfma_f32_16x16x32_bf16 v[54:57], v[150:153], v[172:175], v[54:57]
	v_mfma_f32_16x16x32_bf16 v[50:53], v[164:167], v[172:175], v[50:53]
	v_mfma_f32_16x16x32_bf16 v[38:41], v[150:153], v[180:183], v[38:41]
	v_mfma_f32_16x16x32_bf16 v[34:37], v[164:167], v[180:183], v[34:37]
	v_mfma_f32_16x16x32_bf16 v[22:25], v[150:153], v[188:191], v[22:25]
	v_mfma_f32_16x16x32_bf16 v[18:21], v[164:167], v[188:191], v[18:21]
	v_mfma_f32_16x16x32_bf16 v[6:9], v[150:153], v[200:203], v[6:9]
	v_mfma_f32_16x16x32_bf16 v[2:5], v[164:167], v[200:203], v[2:5]
	s_barrier
	s_setprio 0
	s_add_i32 s59, s59, 2
	s_addk_i32 s2, 0x100
	s_addk_i32 s3, 0x100
	s_cmp_gt_u32 s59, 13
	s_cbranch_scc0 .LBB0_1235
	s_mov_b32 m0, s41
	s_nop 0
	buffer_load_dwordx4 v0, s[20:23], s61 offen lds
	s_mov_b32 m0, s33
	s_nop 0
	buffer_load_dwordx4 v159, s[20:23], s61 offen lds
	v_readlane_b32 s2, v251, 45
	v_readlane_b32 s3, v251, 46
	s_and_b64 vcc, exec, s[2:3]
	s_cbranch_vccz .LBB0_1238
	s_barrier

; #define PG8_WAIT_V(n) asm volatile("s_waitcnt vmcnt(" #n ")" ::: "memory")
; template <class Epi, bool ALIGN_EPI, bool SP2, class Hook>
; __device__ __forceinline__ void gemm_phase(LAS unsigned char* lds, const Gemm g, const StaticOrder& S, const Epi& E, Acc& acc, const bool fresh, const Hook& H, const int wave_id) {
;     ...
;         if constexpr (SP2 && Epi::NSTORE > 0) {
;             const Src a1 = cA + kstep, a2 = cA + 2 * kstep, b2 = cB + 2 * kstep, a3 = a2 + kstep, b3 = b2 + kstep;
;             if constexpr (Epi::NSTORE == 16) PG8_TRIP_SP2(PG8_WAIT_V(24)); else PG8_TRIP_SP2(PG8_WAIT_V(16));
;             t0 = 2;
.LBB0_1452:
	ds_read_b128 v[2:5], v138
	ds_read_b128 v[6:9], v138 offset:1024
	ds_read_b128 v[10:13], v138 offset:2048
	ds_read_b128 v[14:17], v138 offset:3072
	ds_read_b128 v[18:21], v139
	ds_read_b128 v[22:25], v139 offset:1024
	ds_read_b128 v[26:29], v139 offset:2048
	ds_read_b128 v[30:33], v139 offset:3072
	s_or_b32 s3, s50, 0x100
	s_or_b32 s2, s50, 0x180
	s_or_b32 s12, s51, 0x100
	s_or_b32 s13, s50, 0x40080
	s_mov_b32 m0, s45
	ds_read_b128 v[34:37], v137
	ds_read_b128 v[38:41], v137 offset:1024
	ds_read_b128 v[42:45], v137 offset:2048
	ds_read_b128 v[46:49], v137 offset:3072
	ds_read_b128 v[50:53], v137 offset:4096
	ds_read_b128 v[54:57], v137 offset:5120
	ds_read_b128 v[58:61], v137 offset:6144
	ds_read_b128 v[62:65], v137 offset:7168
	buffer_load_dwordx4 v132, s[4:7], s13 offen lds
	s_mov_b32 m0, s46
	s_nop 0
	buffer_load_dwordx4 v134, s[4:7], s13 offen lds
	s_waitcnt vmcnt(16)
	s_waitcnt lgkmcnt(0)
	s_setprio 1
	s_barrier
	v_mfma_f32_16x16x32_bf16 v[90:93], v[2:5], v[58:61], 0
	v_mfma_f32_16x16x32_bf16 v[66:69], v[2:5], v[34:37], 0
	v_mfma_f32_16x16x32_bf16 v[70:73], v[10:13], v[34:37], 0
	v_mfma_f32_16x16x32_bf16 v[74:77], v[2:5], v[42:45], 0
	v_mfma_f32_16x16x32_bf16 v[78:81], v[10:13], v[42:45], 0
	v_mfma_f32_16x16x32_bf16 v[82:85], v[2:5], v[50:53], 0
	v_mfma_f32_16x16x32_bf16 v[86:89], v[10:13], v[50:53], 0
	v_mfma_f32_16x16x32_bf16 v[96:99], v[6:9], v[62:65], v[90:93]
	v_mfma_f32_16x16x32_bf16 v[90:93], v[10:13], v[58:61], 0
	v_mfma_f32_16x16x32_bf16 v[66:69], v[6:9], v[38:41], v[66:69]
	v_mfma_f32_16x16x32_bf16 v[70:73], v[14:17], v[38:41], v[70:73]
	v_mfma_f32_16x16x32_bf16 v[74:77], v[6:9], v[46:49], v[74:77]
	v_mfma_f32_16x16x32_bf16 v[78:81], v[14:17], v[46:49], v[78:81]
	v_mfma_f32_16x16x32_bf16 v[82:85], v[6:9], v[54:57], v[82:85]
	v_mfma_f32_16x16x32_bf16 v[86:89], v[14:17], v[54:57], v[86:89]
	v_mfma_f32_16x16x32_bf16 v[104:107], v[14:17], v[62:65], v[90:93]
	v_mfma_f32_16x16x32_bf16 v[90:93], v[18:21], v[34:37], 0
	v_mfma_f32_16x16x32_bf16 v[34:37], v[26:29], v[34:37], 0
	v_mfma_f32_16x16x32_bf16 v[112:115], v[22:25], v[38:41], v[90:93]
	v_mfma_f32_16x16x32_bf16 v[34:37], v[30:33], v[38:41], v[34:37]
	v_mfma_f32_16x16x32_bf16 v[38:41], v[18:21], v[42:45], 0
	v_mfma_f32_16x16x32_bf16 v[42:45], v[26:29], v[42:45], 0
	v_mfma_f32_16x16x32_bf16 v[38:41], v[22:25], v[46:49], v[38:41]
	v_mfma_f32_16x16x32_bf16 v[42:45], v[30:33], v[46:49], v[42:45]
	v_mfma_f32_16x16x32_bf16 v[46:49], v[18:21], v[50:53], 0
	v_mfma_f32_16x16x32_bf16 v[50:53], v[26:29], v[50:53], 0
	v_mfma_f32_16x16x32_bf16 v[46:49], v[22:25], v[54:57], v[46:49]
	v_mfma_f32_16x16x32_bf16 v[50:53], v[30:33], v[54:57], v[50:53]
	v_mfma_f32_16x16x32_bf16 v[54:57], v[18:21], v[58:61], 0
	v_mfma_f32_16x16x32_bf16 v[58:61], v[26:29], v[58:61], 0
	v_mfma_f32_16x16x32_bf16 v[54:57], v[22:25], v[62:65], v[54:57]
	v_mfma_f32_16x16x32_bf16 v[58:61], v[30:33], v[62:65], v[58:61]
	s_barrier
	s_setprio 0
	s_mov_b32 m0, s92
	ds_read_b128 v[62:65], v137 offset:16384
	ds_read_b128 v[90:93], v137 offset:17408
	ds_read_b128 v[100:103], v137 offset:18432
	ds_read_b128 v[108:111], v137 offset:19456
	ds_read_b128 v[116:119], v137 offset:20480
	ds_read_b128 v[120:123], v137 offset:21504
	ds_read_b128 v[124:127], v137 offset:22528
	ds_read_b128 v[128:131], v137 offset:23552
	buffer_load_dwordx4 v133, s[8:11], s12 offen lds
	s_mov_b32 m0, s93
	s_nop 0
	buffer_load_dwordx4 v135, s[8:11], s12 offen lds
	s_or_b32 s12, s51, 0x40100
	s_mov_b32 m0, s94
	s_nop 0
	buffer_load_dwordx4 v133, s[8:11], s12 offen lds
	s_mov_b32 m0, s95
	s_nop 0
	buffer_load_dwordx4 v135, s[8:11], s12 offen lds
	s_mov_b32 s101, s3
	s_waitcnt vmcnt(14)
	s_waitcnt lgkmcnt(0)
	s_setprio 1
	s_barrier
	v_mfma_f32_16x16x32_bf16 v[142:145], v[2:5], v[62:65], 0
	v_mfma_f32_16x16x32_bf16 v[150:153], v[2:5], v[100:103], 0
	v_mfma_f32_16x16x32_bf16 v[158:161], v[2:5], v[116:119], 0
	v_mfma_f32_16x16x32_bf16 v[2:5], v[2:5], v[124:127], 0
	v_mfma_f32_16x16x32_bf16 v[142:145], v[6:9], v[90:93], v[142:145]
	v_mfma_f32_16x16x32_bf16 v[150:153], v[6:9], v[108:111], v[150:153]
	v_mfma_f32_16x16x32_bf16 v[158:161], v[6:9], v[120:123], v[158:161]
	v_mfma_f32_16x16x32_bf16 v[2:5], v[6:9], v[128:131], v[2:5]
	v_mfma_f32_16x16x32_bf16 v[6:9], v[10:13], v[124:127], 0
	v_mfma_f32_16x16x32_bf16 v[146:149], v[10:13], v[62:65], 0
	v_mfma_f32_16x16x32_bf16 v[154:157], v[10:13], v[100:103], 0
	v_mfma_f32_16x16x32_bf16 v[162:165], v[10:13], v[116:119], 0
	v_mfma_f32_16x16x32_bf16 v[6:9], v[14:17], v[128:131], v[6:9]
	v_mfma_f32_16x16x32_bf16 v[146:149], v[14:17], v[90:93], v[146:149]
	v_mfma_f32_16x16x32_bf16 v[154:157], v[14:17], v[108:111], v[154:157]
	v_mfma_f32_16x16x32_bf16 v[162:165], v[14:17], v[120:123], v[162:165]
	v_mfma_f32_16x16x32_bf16 v[10:13], v[18:21], v[62:65], 0
	v_mfma_f32_16x16x32_bf16 v[166:169], v[22:25], v[90:93], v[10:13]
	v_mfma_f32_16x16x32_bf16 v[10:13], v[26:29], v[62:65], 0
	v_mfma_f32_16x16x32_bf16 v[170:173], v[30:33], v[90:93], v[10:13]
	v_mfma_f32_16x16x32_bf16 v[10:13], v[18:21], v[100:103], 0
	v_mfma_f32_16x16x32_bf16 v[174:177], v[22:25], v[108:111], v[10:13]
	v_mfma_f32_16x16x32_bf16 v[10:13], v[26:29], v[100:103], 0
	v_mfma_f32_16x16x32_bf16 v[178:181], v[30:33], v[108:111], v[10:13]
	v_mfma_f32_16x16x32_bf16 v[10:13], v[18:21], v[116:119], 0
	v_mfma_f32_16x16x32_bf16 v[182:185], v[22:25], v[120:123], v[10:13]
	v_mfma_f32_16x16x32_bf16 v[10:13], v[26:29], v[116:119], 0
	v_mfma_f32_16x16x32_bf16 v[186:189], v[30:33], v[120:123], v[10:13]
	v_mfma_f32_16x16x32_bf16 v[10:13], v[18:21], v[124:127], 0
	v_mfma_f32_16x16x32_bf16 v[16:19], v[22:25], v[128:131], v[10:13]
	v_mfma_f32_16x16x32_bf16 v[10:13], v[26:29], v[124:127], 0
	v_mfma_f32_16x16x32_bf16 v[190:193], v[30:33], v[128:131], v[10:13]
	s_barrier
; __device__ __forceinline__ const bf16_t* selA(const Gemm& g, int s) { return sel3(g.A0, g.A1, g.A2, s); }
; __device__ __forceinline__ const bf16_t* selB(const Gemm& g, int s) { return sel3(g.B0, g.B1, g.B2, s); }
; __device__ __forceinline__ Src make_src(const bf16_t* p, size_t off) { Src s_; s_.r = __builtin_amdgcn_make_buffer_rsrc((void*)p, (short)0, 0x7fffffff, 0x00020000); s_.o = (unsigned)off; return s_; }
; #define PG8_WAIT_V(n) asm volatile("s_waitcnt vmcnt(" #n ")" ::: "memory")
; template <class Epi, bool ALIGN_EPI, bool SP2, class Hook>
; __device__ __forceinline__ void gemm_phase(LAS unsigned char* lds, const Gemm g, const StaticOrder& S, const Epi& E, Acc& acc, const bool fresh, const Hook& H, const int wave_id) {
;     ...
;     for (;;) {
;         const bool has_next = S.next(ui + 1, nxt);
;         const Src nA = has_next ? make_src(selA(g, nxt.seg), (size_t)nxt.pm * tstepA) : cA, nB = has_next ? make_src(selB(g, nxt.seg), (size_t)nxt.pn * tstep) : cB;
;         for (int t = t0; t < nt; t += 2) {
;             const bool last = (t == nt - 2);
;             const Src a1 = cA + (size_t)(t + 1) * kstep;
;             const Src a2 = last ? nA : cA + (size_t)(t + 2) * kstep, b2 = last ? nB : cB + (size_t)(t + 2) * kstep;
;     ...
;         if constexpr (SP2 && Epi::NSTORE > 0) {
;             const Src a1 = cA + kstep, a2 = cA + 2 * kstep, b2 = cB + 2 * kstep, a3 = a2 + kstep, b3 = b2 + kstep;
;             if constexpr (Epi::NSTORE == 16) PG8_TRIP_SP2(PG8_WAIT_V(24)); else PG8_TRIP_SP2(PG8_WAIT_V(16));
;             t0 = 2;
	s_setprio 0
	s_nop 4
	ds_read_b128 v[10:13], v140
	ds_read_b128 v[24:27], v140 offset:1024
	ds_read_b128 v[194:197], v140 offset:2048
	ds_read_b128 v[200:203], v140 offset:3072
	ds_read_b128 v[204:207], v141
	ds_read_b128 v[208:211], v141 offset:1024
	ds_read_b128 v[212:215], v141 offset:2048
	ds_read_b128 v[138:141], v141 offset:3072
	s_or_b32 s3, s50, 0x40100
	s_mov_b32 m0, s37
	ds_read_b128 v[20:23], v137 offset:32768
	ds_read_b128 v[28:31], v137 offset:33792
	ds_read_b128 v[216:219], v137 offset:34816
	ds_read_b128 v[220:223], v137 offset:35840
	ds_read_b128 v[228:231], v137 offset:36864
	ds_read_b128 v[232:235], v137 offset:37888
	ds_read_b128 v[236:239], v137 offset:38912
	ds_read_b128 v[240:243], v137 offset:39936
	s_mov_b32 m0, s44
	s_nop 0
	buffer_load_dwordx4 v132, s[4:7], s101 offen lds
	s_mov_b32 m0, s36
	s_nop 0
	buffer_load_dwordx4 v134, s[4:7], s101 offen lds
	s_mov_b32 m0, s37
	s_nop 0
	buffer_load_dwordx4 v132, s[4:7], s3 offen lds
	s_mov_b32 m0, s38
	s_nop 0
	buffer_load_dwordx4 v134, s[4:7], s3 offen lds
	s_waitcnt vmcnt(8)
	s_waitcnt lgkmcnt(0)
	s_setprio 1
	s_barrier
	v_mfma_f32_16x16x32_bf16 v[62:65], v[10:13], v[20:23], v[66:69]
	v_mfma_f32_16x16x32_bf16 v[124:127], v[24:27], v[28:31], v[62:65]
	v_mfma_f32_16x16x32_bf16 v[62:65], v[194:197], v[20:23], v[70:73]
	v_mfma_f32_16x16x32_bf16 v[116:119], v[200:203], v[28:31], v[62:65]
	v_mfma_f32_16x16x32_bf16 v[62:65], v[10:13], v[216:219], v[74:77]
	v_mfma_f32_16x16x32_bf16 v[108:111], v[24:27], v[220:223], v[62:65]
	v_mfma_f32_16x16x32_bf16 v[62:65], v[194:197], v[216:219], v[78:81]
	v_mfma_f32_16x16x32_bf16 v[100:103], v[200:203], v[220:223], v[62:65]
	v_mfma_f32_16x16x32_bf16 v[62:65], v[10:13], v[228:231], v[82:85]
	v_mfma_f32_16x16x32_bf16 v[92:95], v[24:27], v[232:235], v[62:65]
	v_mfma_f32_16x16x32_bf16 v[62:65], v[194:197], v[228:231], v[86:89]
	v_mfma_f32_16x16x32_bf16 v[84:87], v[200:203], v[232:235], v[62:65]
	v_mfma_f32_16x16x32_bf16 v[62:65], v[10:13], v[236:239], v[96:99]
	v_mfma_f32_16x16x32_bf16 v[76:79], v[24:27], v[240:243], v[62:65]
	v_mfma_f32_16x16x32_bf16 v[62:65], v[194:197], v[236:239], v[104:107]
	v_mfma_f32_16x16x32_bf16 v[64:67], v[200:203], v[240:243], v[62:65]
	v_mfma_f32_16x16x32_bf16 v[68:71], v[204:207], v[20:23], v[112:115]
	v_mfma_f32_16x16x32_bf16 v[20:23], v[212:215], v[20:23], v[34:37]
	v_mfma_f32_16x16x32_bf16 v[120:123], v[138:141], v[28:31], v[20:23]
	v_mfma_f32_16x16x32_bf16 v[20:23], v[204:207], v[216:219], v[38:41]
	v_mfma_f32_16x16x32_bf16 v[112:115], v[208:211], v[220:223], v[20:23]
	v_mfma_f32_16x16x32_bf16 v[20:23], v[212:215], v[216:219], v[42:45]
	v_mfma_f32_16x16x32_bf16 v[104:107], v[138:141], v[220:223], v[20:23]
	v_mfma_f32_16x16x32_bf16 v[20:23], v[204:207], v[228:231], v[46:49]
	v_mfma_f32_16x16x32_bf16 v[96:99], v[208:211], v[232:235], v[20:23]
	v_mfma_f32_16x16x32_bf16 v[20:23], v[212:215], v[228:231], v[50:53]
	v_mfma_f32_16x16x32_bf16 v[88:91], v[138:141], v[232:235], v[20:23]
	v_mfma_f32_16x16x32_bf16 v[20:23], v[204:207], v[236:239], v[54:57]
	v_mfma_f32_16x16x32_bf16 v[80:83], v[208:211], v[240:243], v[20:23]
	v_mfma_f32_16x16x32_bf16 v[20:23], v[212:215], v[236:239], v[58:61]
	v_mfma_f32_16x16x32_bf16 v[128:131], v[208:211], v[28:31], v[68:71]
	v_mfma_f32_16x16x32_bf16 v[68:71], v[138:141], v[240:243], v[20:23]
	s_barrier
	s_setprio 0
	s_mov_b32 m0, s39
	s_or_b32 s3, s51, 0x180
	ds_read_b128 v[32:35], v137 offset:49152
	ds_read_b128 v[40:43], v137 offset:50176
	ds_read_b128 v[216:219], v137 offset:51200
	ds_read_b128 v[220:223], v137 offset:52224
	ds_read_b128 v[228:231], v137 offset:53248
	ds_read_b128 v[232:235], v137 offset:54272
	ds_read_b128 v[236:239], v137 offset:55296
	ds_read_b128 v[240:243], v137 offset:56320
	buffer_load_dwordx4 v133, s[8:11], s3 offen lds
	s_mov_b32 m0, s40
	s_nop 0
	buffer_load_dwordx4 v135, s[8:11], s3 offen lds
	s_or_b32 s3, s51, 0x40180
	s_mov_b32 m0, s43
	s_nop 0
	buffer_load_dwordx4 v133, s[8:11], s3 offen lds
	s_mov_b32 m0, s42
	s_nop 0
	buffer_load_dwordx4 v135, s[8:11], s3 offen lds
	s_waitcnt vmcnt(6)
	s_waitcnt lgkmcnt(0)
	s_setprio 1
	s_barrier
	v_mfma_f32_16x16x32_bf16 v[20:23], v[10:13], v[32:35], v[142:145]
	v_mfma_f32_16x16x32_bf16 v[60:63], v[24:27], v[40:43], v[20:23]
	v_mfma_f32_16x16x32_bf16 v[20:23], v[194:197], v[32:35], v[146:149]
	v_mfma_f32_16x16x32_bf16 v[52:55], v[200:203], v[40:43], v[20:23]
	v_mfma_f32_16x16x32_bf16 v[20:23], v[10:13], v[216:219], v[150:153]
	v_mfma_f32_16x16x32_bf16 v[44:47], v[24:27], v[220:223], v[20:23]
	v_mfma_f32_16x16x32_bf16 v[20:23], v[194:197], v[216:219], v[154:157]
	v_mfma_f32_16x16x32_bf16 v[36:39], v[200:203], v[220:223], v[20:23]
	v_mfma_f32_16x16x32_bf16 v[20:23], v[10:13], v[228:231], v[158:161]
	v_mfma_f32_16x16x32_bf16 v[2:5], v[10:13], v[236:239], v[2:5]
	v_mfma_f32_16x16x32_bf16 v[28:31], v[24:27], v[232:235], v[20:23]
	v_mfma_f32_16x16x32_bf16 v[20:23], v[194:197], v[228:231], v[162:165]
	v_mfma_f32_16x16x32_bf16 v[12:15], v[24:27], v[240:243], v[2:5]
	v_mfma_f32_16x16x32_bf16 v[2:5], v[194:197], v[236:239], v[6:9]
	v_mfma_f32_16x16x32_bf16 v[20:23], v[200:203], v[232:235], v[20:23]
	v_mfma_f32_16x16x32_bf16 v[4:7], v[200:203], v[240:243], v[2:5]
	v_mfma_f32_16x16x32_bf16 v[8:11], v[204:207], v[32:35], v[166:169]
	v_mfma_f32_16x16x32_bf16 v[72:75], v[208:211], v[40:43], v[8:11]
	v_mfma_f32_16x16x32_bf16 v[8:11], v[212:215], v[32:35], v[170:173]
	v_mfma_f32_16x16x32_bf16 v[56:59], v[138:141], v[40:43], v[8:11]
	v_mfma_f32_16x16x32_bf16 v[8:11], v[204:207], v[216:219], v[174:177]
	v_mfma_f32_16x16x32_bf16 v[48:51], v[208:211], v[220:223], v[8:11]
	v_mfma_f32_16x16x32_bf16 v[8:11], v[212:215], v[216:219], v[178:181]
	v_mfma_f32_16x16x32_bf16 v[40:43], v[138:141], v[220:223], v[8:11]
	v_mfma_f32_16x16x32_bf16 v[8:11], v[204:207], v[228:231], v[182:185]
	v_mfma_f32_16x16x32_bf16 v[32:35], v[208:211], v[232:235], v[8:11]
	v_mfma_f32_16x16x32_bf16 v[8:11], v[212:215], v[228:231], v[186:189]
	v_mfma_f32_16x16x32_bf16 v[24:27], v[138:141], v[232:235], v[8:11]
	v_mfma_f32_16x16x32_bf16 v[8:11], v[204:207], v[236:239], v[16:19]
	v_mfma_f32_16x16x32_bf16 v[16:19], v[208:211], v[240:243], v[8:11]
	v_mfma_f32_16x16x32_bf16 v[8:11], v[212:215], v[236:239], v[190:193]
	v_mfma_f32_16x16x32_bf16 v[8:11], v[138:141], v[240:243], v[8:11]
	s_barrier
	s_setprio 0
	s_mov_b64 s[2:3], 0
	v_mov_b64_e32 v[234:235], v[226:227]
	v_mov_b32_e32 v226, v0
	v_mov_b64_e32 v[236:237], v[198:199]
	v_mov_b32_e32 v198, v225

; #define PG8_WAIT_V(n) asm volatile("s_waitcnt vmcnt(" #n ")" ::: "memory")
; template <class Epi, bool ALIGN_EPI, bool SP2, class Hook>
; __device__ __forceinline__ void gemm_phase(LAS unsigned char* lds, const Gemm g, const StaticOrder& S, const Epi& E, Acc& acc, const bool fresh, const Hook& H, const int wave_id) {
;     ...
;         for (int t = t0; t < nt; t += 2) {
;             const bool last = (t == nt - 2);
;             const Src a1 = cA + (size_t)(t + 1) * kstep;
;             const Src a2 = last ? nA : cA + (size_t)(t + 2) * kstep, b2 = last ? nB : cB + (size_t)(t + 2) * kstep;
;             const Src a3 = a2 + kstep, b3 = b2 + kstep;
;             if (last && has_next) H(nxt);
;             if constexpr (SP2) {
;             PG8_TRIP_SP2(PG8_WAIT_V(8));
.LBB0_1461:
	s_add_i32 s100, s55, 0xfffc0000
	v_add_u32_e32 v138, 0x10000, v136
	v_add_u32_e32 v139, 0x14000, v136
	ds_read_b128 v[140:143], v138
	ds_read_b128 v[144:147], v138 offset:1024
	ds_read_b128 v[148:151], v138 offset:2048
	ds_read_b128 v[152:155], v138 offset:3072
	ds_read_b128 v[156:159], v139
	ds_read_b128 v[160:163], v139 offset:1024
	ds_read_b128 v[164:167], v139 offset:2048
	ds_read_b128 v[168:171], v139 offset:3072
	s_add_i32 s16, s55, 0xfffc0080
	s_cmp_eq_u32 s54, 12
	s_cselect_b32 s59, s50, s16
	s_cselect_b32 s17, s9, s77
	s_cselect_b32 s16, s8, s76
	s_cselect_b32 s19, s11, s29
	s_cselect_b32 s18, s10, s28
	s_cselect_b32 s57, s51, s56
	s_cselect_b32 s20, s4, s12
	s_cselect_b32 s21, s5, s13
	s_cselect_b32 s22, s6, s14
	s_cselect_b32 s23, s7, s15
	s_or_b32 s58, s59, 0x80
	s_mov_b32 m0, s45
	ds_read_b128 v[172:175], v137
	ds_read_b128 v[176:179], v137 offset:1024
	ds_read_b128 v[180:183], v137 offset:2048
	ds_read_b128 v[184:187], v137 offset:3072
	ds_read_b128 v[188:191], v137 offset:4096
	ds_read_b128 v[192:195], v137 offset:5120
	ds_read_b128 v[200:203], v137 offset:6144
	ds_read_b128 v[204:207], v137 offset:7168
	s_mov_b32 m0, s41
	s_nop 0
	buffer_load_dwordx4 v132, s[12:15], s100 offen lds
	s_mov_b32 m0, s33
	s_nop 0
	buffer_load_dwordx4 v134, s[12:15], s100 offen lds
	s_mov_b32 m0, s45
	s_nop 0
	buffer_load_dwordx4 v132, s[12:15], s55 offen lds
	s_mov_b32 m0, s46
	s_nop 0
	buffer_load_dwordx4 v134, s[12:15], s55 offen lds
	s_waitcnt vmcnt(8)
	s_waitcnt lgkmcnt(0)
	s_setprio 1
	s_barrier
	v_mfma_f32_16x16x32_bf16 v[124:127], v[140:143], v[172:175], v[124:127]
	v_mfma_f32_16x16x32_bf16 v[116:119], v[148:151], v[172:175], v[116:119]
	v_mfma_f32_16x16x32_bf16 v[108:111], v[140:143], v[180:183], v[108:111]
	v_mfma_f32_16x16x32_bf16 v[100:103], v[148:151], v[180:183], v[100:103]
	v_mfma_f32_16x16x32_bf16 v[92:95], v[140:143], v[188:191], v[92:95]
	v_mfma_f32_16x16x32_bf16 v[84:87], v[148:151], v[188:191], v[84:87]
	v_mfma_f32_16x16x32_bf16 v[76:79], v[140:143], v[200:203], v[76:79]
	v_mfma_f32_16x16x32_bf16 v[64:67], v[148:151], v[200:203], v[64:67]
	v_mfma_f32_16x16x32_bf16 v[124:127], v[144:147], v[176:179], v[124:127]
	v_mfma_f32_16x16x32_bf16 v[116:119], v[152:155], v[176:179], v[116:119]
	v_mfma_f32_16x16x32_bf16 v[108:111], v[144:147], v[184:187], v[108:111]
	v_mfma_f32_16x16x32_bf16 v[100:103], v[152:155], v[184:187], v[100:103]
	v_mfma_f32_16x16x32_bf16 v[92:95], v[144:147], v[192:195], v[92:95]
	v_mfma_f32_16x16x32_bf16 v[84:87], v[152:155], v[192:195], v[84:87]
	v_mfma_f32_16x16x32_bf16 v[76:79], v[144:147], v[204:207], v[76:79]
	v_mfma_f32_16x16x32_bf16 v[64:67], v[152:155], v[204:207], v[64:67]
	v_mfma_f32_16x16x32_bf16 v[128:131], v[156:159], v[172:175], v[128:131]
	v_mfma_f32_16x16x32_bf16 v[120:123], v[164:167], v[172:175], v[120:123]
	v_mfma_f32_16x16x32_bf16 v[112:115], v[156:159], v[180:183], v[112:115]
	v_mfma_f32_16x16x32_bf16 v[104:107], v[164:167], v[180:183], v[104:107]
	v_mfma_f32_16x16x32_bf16 v[96:99], v[156:159], v[188:191], v[96:99]
	v_mfma_f32_16x16x32_bf16 v[88:91], v[164:167], v[188:191], v[88:91]
	v_mfma_f32_16x16x32_bf16 v[80:83], v[156:159], v[200:203], v[80:83]
	v_mfma_f32_16x16x32_bf16 v[68:71], v[164:167], v[200:203], v[68:71]
	v_mfma_f32_16x16x32_bf16 v[128:131], v[160:163], v[176:179], v[128:131]
	v_mfma_f32_16x16x32_bf16 v[120:123], v[168:171], v[176:179], v[120:123]
	v_mfma_f32_16x16x32_bf16 v[112:115], v[160:163], v[184:187], v[112:115]
	v_mfma_f32_16x16x32_bf16 v[104:107], v[168:171], v[184:187], v[104:107]
	v_mfma_f32_16x16x32_bf16 v[96:99], v[160:163], v[192:195], v[96:99]
	v_mfma_f32_16x16x32_bf16 v[88:91], v[168:171], v[192:195], v[88:91]
	v_mfma_f32_16x16x32_bf16 v[80:83], v[160:163], v[204:207], v[80:83]
	v_mfma_f32_16x16x32_bf16 v[68:71], v[168:171], v[204:207], v[68:71]
	s_barrier
	s_setprio 0
	s_mov_b32 m0, s92
	ds_read_b128 v[172:175], v137 offset:16384
	ds_read_b128 v[176:179], v137 offset:17408
	ds_read_b128 v[180:183], v137 offset:18432
	ds_read_b128 v[184:187], v137 offset:19456
	ds_read_b128 v[188:191], v137 offset:20480
	ds_read_b128 v[192:195], v137 offset:21504
	ds_read_b128 v[200:203], v137 offset:22528
	ds_read_b128 v[204:207], v137 offset:23552
	buffer_load_dwordx4 v133, s[16:19], s57 offen lds
	s_mov_b32 m0, s93
	s_add_i32 s60, s57, 0x40000
	buffer_load_dwordx4 v135, s[16:19], s57 offen lds
	s_mov_b32 m0, s94
	s_nop 0
	buffer_load_dwordx4 v133, s[16:19], s60 offen lds
	s_mov_b32 m0, s95
	s_nop 0
	buffer_load_dwordx4 v135, s[16:19], s60 offen lds
	s_mov_b32 s101, s59
	s_waitcnt vmcnt(6)
	s_waitcnt lgkmcnt(0)
	s_setprio 1
	s_barrier
; #define PG8_WAIT_V(n) asm volatile("s_waitcnt vmcnt(" #n ")" ::: "memory")
; template <class Epi, bool ALIGN_EPI, bool SP2, class Hook>
; __device__ __forceinline__ void gemm_phase(LAS unsigned char* lds, const Gemm g, const StaticOrder& S, const Epi& E, Acc& acc, const bool fresh, const Hook& H, const int wave_id) {
;     ...
;         for (int t = t0; t < nt; t += 2) {
;             const bool last = (t == nt - 2);
;             const Src a1 = cA + (size_t)(t + 1) * kstep;
;             const Src a2 = last ? nA : cA + (size_t)(t + 2) * kstep, b2 = last ? nB : cB + (size_t)(t + 2) * kstep;
;             const Src a3 = a2 + kstep, b3 = b2 + kstep;
;             if (last && has_next) H(nxt);
;             if constexpr (SP2) {
;             PG8_TRIP_SP2(PG8_WAIT_V(8));
	v_mfma_f32_16x16x32_bf16 v[60:63], v[140:143], v[172:175], v[60:63]
	v_mfma_f32_16x16x32_bf16 v[52:55], v[148:151], v[172:175], v[52:55]
	v_mfma_f32_16x16x32_bf16 v[44:47], v[140:143], v[180:183], v[44:47]
	v_mfma_f32_16x16x32_bf16 v[36:39], v[148:151], v[180:183], v[36:39]
	v_mfma_f32_16x16x32_bf16 v[28:31], v[140:143], v[188:191], v[28:31]
	v_mfma_f32_16x16x32_bf16 v[20:23], v[148:151], v[188:191], v[20:23]
	v_mfma_f32_16x16x32_bf16 v[12:15], v[140:143], v[200:203], v[12:15]
	v_mfma_f32_16x16x32_bf16 v[2:5], v[148:151], v[200:203], v[4:7]
	v_mfma_f32_16x16x32_bf16 v[60:63], v[144:147], v[176:179], v[60:63]
	v_mfma_f32_16x16x32_bf16 v[52:55], v[152:155], v[176:179], v[52:55]
	v_mfma_f32_16x16x32_bf16 v[44:47], v[144:147], v[184:187], v[44:47]
	v_mfma_f32_16x16x32_bf16 v[36:39], v[152:155], v[184:187], v[36:39]
	v_mfma_f32_16x16x32_bf16 v[28:31], v[144:147], v[192:195], v[28:31]
	v_mfma_f32_16x16x32_bf16 v[20:23], v[152:155], v[192:195], v[20:23]
	v_mfma_f32_16x16x32_bf16 v[12:15], v[144:147], v[204:207], v[12:15]
	v_mfma_f32_16x16x32_bf16 v[2:5], v[152:155], v[204:207], v[2:5]
	v_mfma_f32_16x16x32_bf16 v[72:75], v[156:159], v[172:175], v[72:75]
	v_mfma_f32_16x16x32_bf16 v[56:59], v[164:167], v[172:175], v[56:59]
	v_mfma_f32_16x16x32_bf16 v[48:51], v[156:159], v[180:183], v[48:51]
	v_mfma_f32_16x16x32_bf16 v[40:43], v[164:167], v[180:183], v[40:43]
	v_mfma_f32_16x16x32_bf16 v[32:35], v[156:159], v[188:191], v[32:35]
	v_mfma_f32_16x16x32_bf16 v[24:27], v[164:167], v[188:191], v[24:27]
	v_mfma_f32_16x16x32_bf16 v[16:19], v[156:159], v[200:203], v[16:19]
	v_mfma_f32_16x16x32_bf16 v[6:9], v[164:167], v[200:203], v[8:11]
	v_mfma_f32_16x16x32_bf16 v[72:75], v[160:163], v[176:179], v[72:75]
	v_mfma_f32_16x16x32_bf16 v[56:59], v[168:171], v[176:179], v[56:59]
	v_mfma_f32_16x16x32_bf16 v[48:51], v[160:163], v[184:187], v[48:51]
	v_mfma_f32_16x16x32_bf16 v[40:43], v[168:171], v[184:187], v[40:43]
	v_mfma_f32_16x16x32_bf16 v[32:35], v[160:163], v[192:195], v[32:35]
	v_mfma_f32_16x16x32_bf16 v[24:27], v[168:171], v[192:195], v[24:27]
	v_mfma_f32_16x16x32_bf16 v[16:19], v[160:163], v[204:207], v[16:19]
	v_mfma_f32_16x16x32_bf16 v[8:11], v[168:171], v[204:207], v[6:9]
	s_barrier
	s_setprio 0
	v_add_u32_e32 v140, 0x18000, v136
	v_add_u32_e32 v141, 0x1c000, v136
	ds_read_b128 v[142:145], v140
	ds_read_b128 v[146:149], v140 offset:1024
	ds_read_b128 v[150:153], v140 offset:2048
	ds_read_b128 v[154:157], v140 offset:3072
	ds_read_b128 v[158:161], v141
	ds_read_b128 v[162:165], v141 offset:1024
	ds_read_b128 v[166:169], v141 offset:2048
	ds_read_b128 v[170:173], v141 offset:3072
	s_add_i32 s59, s59, 0x40000
	s_mov_b32 m0, s37
	ds_read_b128 v[174:177], v137 offset:32768
	ds_read_b128 v[178:181], v137 offset:33792
	ds_read_b128 v[182:185], v137 offset:34816
	ds_read_b128 v[186:189], v137 offset:35840
	ds_read_b128 v[190:193], v137 offset:36864
	ds_read_b128 v[194:197], v137 offset:37888
	ds_read_b128 v[200:203], v137 offset:38912
	ds_read_b128 v[204:207], v137 offset:39936
	s_mov_b32 m0, s44
	s_nop 0
	buffer_load_dwordx4 v132, s[20:23], s101 offen lds
	s_mov_b32 m0, s36
	s_nop 0
	buffer_load_dwordx4 v134, s[20:23], s101 offen lds
	s_mov_b32 m0, s37
	s_nop 0
	buffer_load_dwordx4 v132, s[20:23], s59 offen lds
	s_mov_b32 m0, s38
	s_nop 0
	buffer_load_dwordx4 v134, s[20:23], s59 offen lds
	s_waitcnt vmcnt(8)
	s_waitcnt lgkmcnt(0)
	s_setprio 1
	s_barrier
	v_mfma_f32_16x16x32_bf16 v[124:127], v[142:145], v[174:177], v[124:127]
	v_mfma_f32_16x16x32_bf16 v[116:119], v[150:153], v[174:177], v[116:119]
	v_mfma_f32_16x16x32_bf16 v[108:111], v[142:145], v[182:185], v[108:111]
	v_mfma_f32_16x16x32_bf16 v[100:103], v[150:153], v[182:185], v[100:103]
	v_mfma_f32_16x16x32_bf16 v[92:95], v[142:145], v[190:193], v[92:95]
	v_mfma_f32_16x16x32_bf16 v[84:87], v[150:153], v[190:193], v[84:87]
	v_mfma_f32_16x16x32_bf16 v[76:79], v[142:145], v[200:203], v[76:79]
	v_mfma_f32_16x16x32_bf16 v[64:67], v[150:153], v[200:203], v[64:67]
	v_mfma_f32_16x16x32_bf16 v[124:127], v[146:149], v[178:181], v[124:127]
	v_mfma_f32_16x16x32_bf16 v[116:119], v[154:157], v[178:181], v[116:119]
	v_mfma_f32_16x16x32_bf16 v[108:111], v[146:149], v[186:189], v[108:111]
	v_mfma_f32_16x16x32_bf16 v[100:103], v[154:157], v[186:189], v[100:103]
	v_mfma_f32_16x16x32_bf16 v[92:95], v[146:149], v[194:197], v[92:95]
	v_mfma_f32_16x16x32_bf16 v[84:87], v[154:157], v[194:197], v[84:87]
	v_mfma_f32_16x16x32_bf16 v[76:79], v[146:149], v[204:207], v[76:79]
	v_mfma_f32_16x16x32_bf16 v[64:67], v[154:157], v[204:207], v[64:67]
	v_mfma_f32_16x16x32_bf16 v[128:131], v[158:161], v[174:177], v[128:131]
	v_mfma_f32_16x16x32_bf16 v[120:123], v[166:169], v[174:177], v[120:123]
	v_mfma_f32_16x16x32_bf16 v[112:115], v[158:161], v[182:185], v[112:115]
	v_mfma_f32_16x16x32_bf16 v[104:107], v[166:169], v[182:185], v[104:107]
	v_mfma_f32_16x16x32_bf16 v[96:99], v[158:161], v[190:193], v[96:99]
	v_mfma_f32_16x16x32_bf16 v[88:91], v[166:169], v[190:193], v[88:91]
	v_mfma_f32_16x16x32_bf16 v[80:83], v[158:161], v[200:203], v[80:83]
	v_mfma_f32_16x16x32_bf16 v[68:71], v[166:169], v[200:203], v[68:71]
	v_mfma_f32_16x16x32_bf16 v[128:131], v[162:165], v[178:181], v[128:131]
	v_mfma_f32_16x16x32_bf16 v[120:123], v[170:173], v[178:181], v[120:123]
	v_mfma_f32_16x16x32_bf16 v[112:115], v[162:165], v[186:189], v[112:115]
	v_mfma_f32_16x16x32_bf16 v[104:107], v[170:173], v[186:189], v[104:107]
	v_mfma_f32_16x16x32_bf16 v[96:99], v[162:165], v[194:197], v[96:99]
	v_mfma_f32_16x16x32_bf16 v[88:91], v[170:173], v[194:197], v[88:91]
	v_mfma_f32_16x16x32_bf16 v[80:83], v[162:165], v[204:207], v[80:83]
	v_mfma_f32_16x16x32_bf16 v[68:71], v[170:173], v[204:207], v[68:71]
	s_barrier
; #define PG8_STAGE(bufoff, gbase, voff) do { const Src _g = (gbase); _Pragma("unroll") for (int _i = 0; _i < 2; ++_i) \
;         __builtin_amdgcn_raw_ptr_buffer_load_lds(_g.r, (LAS unsigned*)(lds + (bufoff) + ldsw + _i * 8192), 16, (voff)[_i], _g.o, 0, 0); } while (0)
; #define PG8_WAIT_V(n) asm volatile("s_waitcnt vmcnt(" #n ")" ::: "memory")
; template <class Epi, bool ALIGN_EPI, bool SP2, class Hook>
; __device__ __forceinline__ void gemm_phase(LAS unsigned char* lds, const Gemm g, const StaticOrder& S, const Epi& E, Acc& acc, const bool fresh, const Hook& H, const int wave_id) {
;     ...
;         for (int t = t0; t < nt; t += 2) {
;             const bool last = (t == nt - 2);
;             const Src a1 = cA + (size_t)(t + 1) * kstep;
;             const Src a2 = last ? nA : cA + (size_t)(t + 2) * kstep, b2 = last ? nB : cB + (size_t)(t + 2) * kstep;
;             const Src a3 = a2 + kstep, b3 = b2 + kstep;
;             if (last && has_next) H(nxt);
;             if constexpr (SP2) {
;             PG8_TRIP_SP2(PG8_WAIT_V(8));
;             } else {
;             PG8_LDB(B0, 0, 0); PG8_SCHED; PG8_LDA(At, 0, 0); PG8_STAGE(PG8_SA(1, 1), a1 + hstepA, voffA);
;             PG8_WAIT_L(8); PG8_BAR; PG8_WAIT_L(0); PG8_MMA(0, 0, At, B0); PG8_BAR; PG8_SCHED;
;             PG8_LDB(B1, 0, 1); PG8_STAGE(PG8_SB(0, 0), b2, voffB);
;             PG8_BAR; PG8_WAIT_L(0); PG8_MMA(0, 1, At, B1); PG8_BAR;
;             PG8_LDA(At, 0, 1); PG8_STAGE(PG8_SA(0, 0), a2, voffA);
;             PG8_BAR; PG8_WAIT_L(0); PG8_MMA(1, 0, At, B0); PG8_BAR; PG8_SCHED;
;             PG8_STAGE(PG8_SB(0, 1), b2 + hstep, voffB);
;             PG8_WAIT_V(6); PG8_BAR; PG8_MMA(1, 1, At, B1); PG8_BAR;
;             PG8_LDB(B0, 1, 0); PG8_SCHED; PG8_LDA(At, 1, 0); PG8_STAGE(PG8_SA(0, 1), a2 + hstepA, voffA);
;             PG8_WAIT_L(8); PG8_BAR; PG8_WAIT_L(0); PG8_MMA(0, 0, At, B0); PG8_BAR; PG8_SCHED;
;             PG8_LDB(B1, 1, 1); PG8_STAGE(PG8_SB(1, 0), b3, voffB);
;             PG8_BAR; PG8_WAIT_L(0); PG8_MMA(0, 1, At, B1); PG8_BAR;
;             PG8_LDA(At, 1, 1); PG8_STAGE(PG8_SA(1, 0), a3, voffA);
;             PG8_BAR; PG8_WAIT_L(0); PG8_MMA(1, 0, At, B0); PG8_BAR; PG8_SCHED;
;             PG8_STAGE(PG8_SB(1, 1), b3 + hstep, voffB);
;             PG8_WAIT_V(6); PG8_BAR; PG8_MMA(1, 1, At, B1); PG8_BAR;
;             }
;         }
;         if constexpr (ALIGN_EPI) { if (wr == 0) PG8_BAR; }
	s_setprio 0
	s_mov_b32 m0, s39
	s_or_b32 s59, s57, 0x80
	ds_read_b128 v[174:177], v137 offset:49152
	ds_read_b128 v[178:181], v137 offset:50176
	ds_read_b128 v[182:185], v137 offset:51200
	ds_read_b128 v[186:189], v137 offset:52224
	ds_read_b128 v[190:193], v137 offset:53248
	ds_read_b128 v[194:197], v137 offset:54272
	ds_read_b128 v[200:203], v137 offset:55296
	ds_read_b128 v[204:207], v137 offset:56320
	buffer_load_dwordx4 v133, s[16:19], s59 offen lds
	s_mov_b32 m0, s40
	s_add_i32 s57, s57, 0x40080
	buffer_load_dwordx4 v135, s[16:19], s59 offen lds
	s_mov_b32 m0, s43
	s_nop 0
	buffer_load_dwordx4 v133, s[16:19], s57 offen lds
	s_mov_b32 m0, s42
	s_nop 0
	buffer_load_dwordx4 v135, s[16:19], s57 offen lds
	s_waitcnt vmcnt(6)
	s_waitcnt lgkmcnt(0)
	s_setprio 1
	s_barrier
	v_mfma_f32_16x16x32_bf16 v[60:63], v[142:145], v[174:177], v[60:63]
	v_mfma_f32_16x16x32_bf16 v[52:55], v[150:153], v[174:177], v[52:55]
	v_mfma_f32_16x16x32_bf16 v[44:47], v[142:145], v[182:185], v[44:47]
	v_mfma_f32_16x16x32_bf16 v[36:39], v[150:153], v[182:185], v[36:39]
	v_mfma_f32_16x16x32_bf16 v[28:31], v[142:145], v[190:193], v[28:31]
	v_mfma_f32_16x16x32_bf16 v[20:23], v[150:153], v[190:193], v[20:23]
	v_mfma_f32_16x16x32_bf16 v[12:15], v[142:145], v[200:203], v[12:15]
	v_mfma_f32_16x16x32_bf16 v[2:5], v[150:153], v[200:203], v[2:5]
	v_mfma_f32_16x16x32_bf16 v[60:63], v[146:149], v[178:181], v[60:63]
	v_mfma_f32_16x16x32_bf16 v[52:55], v[154:157], v[178:181], v[52:55]
	v_mfma_f32_16x16x32_bf16 v[44:47], v[146:149], v[186:189], v[44:47]
	v_mfma_f32_16x16x32_bf16 v[36:39], v[154:157], v[186:189], v[36:39]
	v_mfma_f32_16x16x32_bf16 v[28:31], v[146:149], v[194:197], v[28:31]
	v_mfma_f32_16x16x32_bf16 v[20:23], v[154:157], v[194:197], v[20:23]
	v_mfma_f32_16x16x32_bf16 v[12:15], v[146:149], v[204:207], v[12:15]
	v_mfma_f32_16x16x32_bf16 v[4:7], v[154:157], v[204:207], v[2:5]
	v_mfma_f32_16x16x32_bf16 v[72:75], v[158:161], v[174:177], v[72:75]
	v_mfma_f32_16x16x32_bf16 v[56:59], v[166:169], v[174:177], v[56:59]
	v_mfma_f32_16x16x32_bf16 v[48:51], v[158:161], v[182:185], v[48:51]
	v_mfma_f32_16x16x32_bf16 v[40:43], v[166:169], v[182:185], v[40:43]
	v_mfma_f32_16x16x32_bf16 v[32:35], v[158:161], v[190:193], v[32:35]
	v_mfma_f32_16x16x32_bf16 v[24:27], v[166:169], v[190:193], v[24:27]
	v_mfma_f32_16x16x32_bf16 v[16:19], v[158:161], v[200:203], v[16:19]
	v_mfma_f32_16x16x32_bf16 v[8:11], v[166:169], v[200:203], v[8:11]
	v_mfma_f32_16x16x32_bf16 v[72:75], v[162:165], v[178:181], v[72:75]
	v_mfma_f32_16x16x32_bf16 v[56:59], v[170:173], v[178:181], v[56:59]
	v_mfma_f32_16x16x32_bf16 v[48:51], v[162:165], v[186:189], v[48:51]
	v_mfma_f32_16x16x32_bf16 v[40:43], v[170:173], v[186:189], v[40:43]
	v_mfma_f32_16x16x32_bf16 v[32:35], v[162:165], v[194:197], v[32:35]
	v_mfma_f32_16x16x32_bf16 v[24:27], v[170:173], v[194:197], v[24:27]
	v_mfma_f32_16x16x32_bf16 v[16:19], v[162:165], v[204:207], v[16:19]
	v_mfma_f32_16x16x32_bf16 v[8:11], v[170:173], v[204:207], v[8:11]
	s_barrier
	s_setprio 0
	s_add_i32 s54, s54, 2
	s_addk_i32 s55, 0x100
	s_addk_i32 s56, 0x100
	s_cmp_gt_u32 s54, 13
	s_cbranch_scc0 .LBB0_1461
	s_mov_b32 m0, s41
	s_nop 0
	buffer_load_dwordx4 v132, s[20:23], s58 offen lds
	s_mov_b32 m0, s33
	s_nop 0
	buffer_load_dwordx4 v134, s[20:23], s58 offen lds
	v_readlane_b32 s12, v251, 45
	v_readlane_b32 s13, v251, 46
	s_and_b64 vcc, exec, s[12:13]
	s_cbranch_vccz .LBB0_1464
	s_barrier

; #define PG8_WAIT_V(n) asm volatile("s_waitcnt vmcnt(" #n ")" ::: "memory")
; template <class Epi, bool ALIGN_EPI, bool SP2, class Hook>
; __device__ __forceinline__ void gemm_phase(LAS unsigned char* lds, const Gemm g, const StaticOrder& S, const Epi& E, Acc& acc, const bool fresh, const Hook& H, const int wave_id) {
;     ...
;             const bool last = (t == nt - 2);
;             const Src a1 = cA + (size_t)(t + 1) * kstep;
;             const Src a2 = last ? nA : cA + (size_t)(t + 2) * kstep, b2 = last ? nB : cB + (size_t)(t + 2) * kstep;
;             const Src a3 = a2 + kstep, b3 = b2 + kstep;
;             if (last && has_next) H(nxt);
;             if constexpr (SP2) {
;             PG8_TRIP_SP2(PG8_WAIT_V(8));
.LBB0_1572:
	s_add_i32 s100, s2, 0xfff40000
	v_add_u32_e32 v142, 0x10000, v161
	v_add_u32_e32 v163, 0x14000, v161
	ds_read_b128 v[130:133], v142
	ds_read_b128 v[134:137], v142 offset:1024
	ds_read_b128 v[138:141], v142 offset:2048
	ds_read_b128 v[142:145], v142 offset:3072
	ds_read_b128 v[146:149], v163
	ds_read_b128 v[150:153], v163 offset:1024
	ds_read_b128 v[154:157], v163 offset:2048
	ds_read_b128 v[164:167], v163 offset:3072
	s_add_i32 s16, s2, 0xfff40080
	s_cmp_eq_u32 s61, 40
	s_cselect_b32 s64, s57, s16
	s_cselect_b32 s17, s35, s9
	s_cselect_b32 s16, s34, s8
	s_cselect_b32 s19, s51, s53
	s_cselect_b32 s18, s50, s52
	s_cselect_b32 s62, s58, s3
	s_cselect_b32 s20, s10, s12
	s_cselect_b32 s21, s11, s13
	s_cselect_b32 s22, s30, s14
	s_cselect_b32 s23, s31, s15
	s_or_b32 s63, s64, 0x80
	s_mov_b32 m0, s45
	ds_read_b128 v[168:171], v162
	ds_read_b128 v[172:175], v162 offset:1024
	ds_read_b128 v[176:179], v162 offset:2048
	ds_read_b128 v[180:183], v162 offset:3072
	ds_read_b128 v[184:187], v162 offset:4096
	ds_read_b128 v[188:191], v162 offset:5120
	ds_read_b128 v[192:195], v162 offset:6144
	ds_read_b128 v[200:203], v162 offset:7168
	s_mov_b32 m0, s41
	s_nop 0
	buffer_load_dwordx4 v0, s[12:15], s100 offen lds
	s_mov_b32 m0, s33
	s_nop 0
	buffer_load_dwordx4 v159, s[12:15], s100 offen lds
	s_mov_b32 m0, s45
	s_nop 0
	buffer_load_dwordx4 v0, s[12:15], s2 offen lds
	s_mov_b32 m0, s46
	s_nop 0
	buffer_load_dwordx4 v159, s[12:15], s2 offen lds
	s_waitcnt vmcnt(8)
	s_waitcnt lgkmcnt(0)
	s_setprio 1
	s_barrier
	v_mfma_f32_16x16x32_bf16 v[126:129], v[130:133], v[168:171], v[126:129]
	v_mfma_f32_16x16x32_bf16 v[122:125], v[138:141], v[168:171], v[122:125]
	v_mfma_f32_16x16x32_bf16 v[110:113], v[130:133], v[176:179], v[110:113]
	v_mfma_f32_16x16x32_bf16 v[106:109], v[138:141], v[176:179], v[106:109]
	v_mfma_f32_16x16x32_bf16 v[94:97], v[130:133], v[184:187], v[94:97]
	v_mfma_f32_16x16x32_bf16 v[90:93], v[138:141], v[184:187], v[90:93]
	v_mfma_f32_16x16x32_bf16 v[78:81], v[130:133], v[192:195], v[78:81]
	v_mfma_f32_16x16x32_bf16 v[74:77], v[138:141], v[192:195], v[74:77]
	v_mfma_f32_16x16x32_bf16 v[126:129], v[134:137], v[172:175], v[126:129]
	v_mfma_f32_16x16x32_bf16 v[122:125], v[142:145], v[172:175], v[122:125]
	v_mfma_f32_16x16x32_bf16 v[110:113], v[134:137], v[180:183], v[110:113]
	v_mfma_f32_16x16x32_bf16 v[106:109], v[142:145], v[180:183], v[106:109]
	v_mfma_f32_16x16x32_bf16 v[94:97], v[134:137], v[188:191], v[94:97]
	v_mfma_f32_16x16x32_bf16 v[90:93], v[142:145], v[188:191], v[90:93]
	v_mfma_f32_16x16x32_bf16 v[78:81], v[134:137], v[200:203], v[78:81]
	v_mfma_f32_16x16x32_bf16 v[74:77], v[142:145], v[200:203], v[74:77]
	v_mfma_f32_16x16x32_bf16 v[118:121], v[146:149], v[168:171], v[118:121]
	v_mfma_f32_16x16x32_bf16 v[114:117], v[154:157], v[168:171], v[114:117]
	v_mfma_f32_16x16x32_bf16 v[102:105], v[146:149], v[176:179], v[102:105]
	v_mfma_f32_16x16x32_bf16 v[98:101], v[154:157], v[176:179], v[98:101]
	v_mfma_f32_16x16x32_bf16 v[86:89], v[146:149], v[184:187], v[86:89]
	v_mfma_f32_16x16x32_bf16 v[82:85], v[154:157], v[184:187], v[82:85]
	v_mfma_f32_16x16x32_bf16 v[70:73], v[146:149], v[192:195], v[70:73]
	v_mfma_f32_16x16x32_bf16 v[66:69], v[154:157], v[192:195], v[66:69]
	v_mfma_f32_16x16x32_bf16 v[118:121], v[150:153], v[172:175], v[118:121]
	v_mfma_f32_16x16x32_bf16 v[114:117], v[164:167], v[172:175], v[114:117]
	v_mfma_f32_16x16x32_bf16 v[102:105], v[150:153], v[180:183], v[102:105]
	v_mfma_f32_16x16x32_bf16 v[98:101], v[164:167], v[180:183], v[98:101]
	v_mfma_f32_16x16x32_bf16 v[86:89], v[150:153], v[188:191], v[86:89]
	v_mfma_f32_16x16x32_bf16 v[82:85], v[164:167], v[188:191], v[82:85]
	v_mfma_f32_16x16x32_bf16 v[70:73], v[150:153], v[200:203], v[70:73]
	v_mfma_f32_16x16x32_bf16 v[66:69], v[164:167], v[200:203], v[66:69]
	s_barrier
	s_setprio 0
	s_mov_b32 m0, s92
	ds_read_b128 v[168:171], v162 offset:16384
	ds_read_b128 v[172:175], v162 offset:17408
	ds_read_b128 v[176:179], v162 offset:18432
	ds_read_b128 v[180:183], v162 offset:19456
	ds_read_b128 v[184:187], v162 offset:20480
	ds_read_b128 v[188:191], v162 offset:21504
	ds_read_b128 v[192:195], v162 offset:22528
	ds_read_b128 v[200:203], v162 offset:23552
	buffer_load_dwordx4 v158, s[16:19], s62 offen lds
	s_mov_b32 m0, s93
	s_add_i32 s65, s62, 0xb0000
	buffer_load_dwordx4 v160, s[16:19], s62 offen lds
	s_mov_b32 m0, s94
	s_nop 0
	buffer_load_dwordx4 v158, s[16:19], s65 offen lds
	s_mov_b32 m0, s95
	s_nop 0
	buffer_load_dwordx4 v160, s[16:19], s65 offen lds
	s_mov_b32 s101, s64
	s_waitcnt vmcnt(6)
	s_waitcnt lgkmcnt(0)
	s_setprio 1
	s_barrier
	v_mfma_f32_16x16x32_bf16 v[62:65], v[130:133], v[168:171], v[62:65]
	v_mfma_f32_16x16x32_bf16 v[58:61], v[138:141], v[168:171], v[58:61]
	v_mfma_f32_16x16x32_bf16 v[46:49], v[130:133], v[176:179], v[46:49]
	v_mfma_f32_16x16x32_bf16 v[42:45], v[138:141], v[176:179], v[42:45]
	v_mfma_f32_16x16x32_bf16 v[30:33], v[130:133], v[184:187], v[30:33]
	v_mfma_f32_16x16x32_bf16 v[26:29], v[138:141], v[184:187], v[26:29]
	v_mfma_f32_16x16x32_bf16 v[14:17], v[130:133], v[192:195], v[14:17]
	v_mfma_f32_16x16x32_bf16 v[10:13], v[138:141], v[192:195], v[10:13]
	v_mfma_f32_16x16x32_bf16 v[62:65], v[134:137], v[172:175], v[62:65]
	v_mfma_f32_16x16x32_bf16 v[58:61], v[142:145], v[172:175], v[58:61]
	v_mfma_f32_16x16x32_bf16 v[46:49], v[134:137], v[180:183], v[46:49]
	v_mfma_f32_16x16x32_bf16 v[42:45], v[142:145], v[180:183], v[42:45]
	v_mfma_f32_16x16x32_bf16 v[30:33], v[134:137], v[188:191], v[30:33]
	v_mfma_f32_16x16x32_bf16 v[26:29], v[142:145], v[188:191], v[26:29]
	v_mfma_f32_16x16x32_bf16 v[14:17], v[134:137], v[200:203], v[14:17]
	v_mfma_f32_16x16x32_bf16 v[10:13], v[142:145], v[200:203], v[10:13]
	v_mfma_f32_16x16x32_bf16 v[54:57], v[146:149], v[168:171], v[54:57]
	v_mfma_f32_16x16x32_bf16 v[50:53], v[154:157], v[168:171], v[50:53]
	v_mfma_f32_16x16x32_bf16 v[38:41], v[146:149], v[176:179], v[38:41]
	v_mfma_f32_16x16x32_bf16 v[34:37], v[154:157], v[176:179], v[34:37]
	v_mfma_f32_16x16x32_bf16 v[22:25], v[146:149], v[184:187], v[22:25]
	v_mfma_f32_16x16x32_bf16 v[18:21], v[154:157], v[184:187], v[18:21]
	v_mfma_f32_16x16x32_bf16 v[6:9], v[146:149], v[192:195], v[6:9]
	v_mfma_f32_16x16x32_bf16 v[2:5], v[154:157], v[192:195], v[2:5]
	v_mfma_f32_16x16x32_bf16 v[54:57], v[150:153], v[172:175], v[54:57]
	v_mfma_f32_16x16x32_bf16 v[50:53], v[164:167], v[172:175], v[50:53]
	v_mfma_f32_16x16x32_bf16 v[38:41], v[150:153], v[180:183], v[38:41]
	v_mfma_f32_16x16x32_bf16 v[34:37], v[164:167], v[180:183], v[34:37]
	v_mfma_f32_16x16x32_bf16 v[22:25], v[150:153], v[188:191], v[22:25]
	v_mfma_f32_16x16x32_bf16 v[18:21], v[164:167], v[188:191], v[18:21]
	v_mfma_f32_16x16x32_bf16 v[6:9], v[150:153], v[200:203], v[6:9]
	v_mfma_f32_16x16x32_bf16 v[2:5], v[164:167], v[200:203], v[2:5]
	s_barrier
	s_setprio 0
	v_add_u32_e32 v142, 0x18000, v161
	v_add_u32_e32 v163, 0x1c000, v161
	ds_read_b128 v[130:133], v142
	ds_read_b128 v[134:137], v142 offset:1024
	ds_read_b128 v[138:141], v142 offset:2048
	ds_read_b128 v[142:145], v142 offset:3072
	ds_read_b128 v[146:149], v163
	ds_read_b128 v[150:153], v163 offset:1024
	ds_read_b128 v[154:157], v163 offset:2048
	ds_read_b128 v[164:167], v163 offset:3072
	s_add_i32 s64, s64, 0xc0000
	s_mov_b32 m0, s37
	ds_read_b128 v[168:171], v162 offset:32768
	ds_read_b128 v[172:175], v162 offset:33792
	ds_read_b128 v[176:179], v162 offset:34816
	ds_read_b128 v[180:183], v162 offset:35840
	ds_read_b128 v[184:187], v162 offset:36864
	ds_read_b128 v[188:191], v162 offset:37888
	ds_read_b128 v[192:195], v162 offset:38912
	ds_read_b128 v[200:203], v162 offset:39936
	s_mov_b32 m0, s44
	s_nop 0
	buffer_load_dwordx4 v0, s[20:23], s101 offen lds
	s_mov_b32 m0, s36
	s_nop 0
	buffer_load_dwordx4 v159, s[20:23], s101 offen lds
	s_mov_b32 m0, s37
	s_nop 0
	buffer_load_dwordx4 v0, s[20:23], s64 offen lds
	s_mov_b32 m0, s38
	s_nop 0
	buffer_load_dwordx4 v159, s[20:23], s64 offen lds
	s_waitcnt vmcnt(8)
	s_waitcnt lgkmcnt(0)
	s_setprio 1
	s_barrier
	v_mfma_f32_16x16x32_bf16 v[126:129], v[130:133], v[168:171], v[126:129]
	v_mfma_f32_16x16x32_bf16 v[122:125], v[138:141], v[168:171], v[122:125]
	v_mfma_f32_16x16x32_bf16 v[110:113], v[130:133], v[176:179], v[110:113]
	v_mfma_f32_16x16x32_bf16 v[106:109], v[138:141], v[176:179], v[106:109]
	v_mfma_f32_16x16x32_bf16 v[94:97], v[130:133], v[184:187], v[94:97]
	v_mfma_f32_16x16x32_bf16 v[90:93], v[138:141], v[184:187], v[90:93]
	v_mfma_f32_16x16x32_bf16 v[78:81], v[130:133], v[192:195], v[78:81]
	v_mfma_f32_16x16x32_bf16 v[74:77], v[138:141], v[192:195], v[74:77]
	v_mfma_f32_16x16x32_bf16 v[126:129], v[134:137], v[172:175], v[126:129]
	v_mfma_f32_16x16x32_bf16 v[122:125], v[142:145], v[172:175], v[122:125]
	v_mfma_f32_16x16x32_bf16 v[110:113], v[134:137], v[180:183], v[110:113]
	v_mfma_f32_16x16x32_bf16 v[106:109], v[142:145], v[180:183], v[106:109]
	v_mfma_f32_16x16x32_bf16 v[94:97], v[134:137], v[188:191], v[94:97]
	v_mfma_f32_16x16x32_bf16 v[90:93], v[142:145], v[188:191], v[90:93]
	v_mfma_f32_16x16x32_bf16 v[78:81], v[134:137], v[200:203], v[78:81]
	v_mfma_f32_16x16x32_bf16 v[74:77], v[142:145], v[200:203], v[74:77]
	v_mfma_f32_16x16x32_bf16 v[118:121], v[146:149], v[168:171], v[118:121]
	v_mfma_f32_16x16x32_bf16 v[114:117], v[154:157], v[168:171], v[114:117]
	v_mfma_f32_16x16x32_bf16 v[102:105], v[146:149], v[176:179], v[102:105]
	v_mfma_f32_16x16x32_bf16 v[98:101], v[154:157], v[176:179], v[98:101]
	v_mfma_f32_16x16x32_bf16 v[86:89], v[146:149], v[184:187], v[86:89]
	v_mfma_f32_16x16x32_bf16 v[82:85], v[154:157], v[184:187], v[82:85]
	v_mfma_f32_16x16x32_bf16 v[70:73], v[146:149], v[192:195], v[70:73]
	v_mfma_f32_16x16x32_bf16 v[66:69], v[154:157], v[192:195], v[66:69]
	v_mfma_f32_16x16x32_bf16 v[118:121], v[150:153], v[172:175], v[118:121]
	v_mfma_f32_16x16x32_bf16 v[114:117], v[164:167], v[172:175], v[114:117]
	v_mfma_f32_16x16x32_bf16 v[102:105], v[150:153], v[180:183], v[102:105]
	v_mfma_f32_16x16x32_bf16 v[98:101], v[164:167], v[180:183], v[98:101]
	v_mfma_f32_16x16x32_bf16 v[86:89], v[150:153], v[188:191], v[86:89]
	v_mfma_f32_16x16x32_bf16 v[82:85], v[164:167], v[188:191], v[82:85]
	v_mfma_f32_16x16x32_bf16 v[70:73], v[150:153], v[200:203], v[70:73]
	v_mfma_f32_16x16x32_bf16 v[66:69], v[164:167], v[200:203], v[66:69]
	s_barrier
; #define PG8_WAIT_V(n) asm volatile("s_waitcnt vmcnt(" #n ")" ::: "memory")
; template <class Epi, bool ALIGN_EPI, bool SP2, class Hook>
; __device__ __forceinline__ void gemm_phase(LAS unsigned char* lds, const Gemm g, const StaticOrder& S, const Epi& E, Acc& acc, const bool fresh, const Hook& H, const int wave_id) {
;     ...
;         for (int t = t0; t < nt; t += 2) {
;             const bool last = (t == nt - 2);
;             const Src a1 = cA + (size_t)(t + 1) * kstep;
;             const Src a2 = last ? nA : cA + (size_t)(t + 2) * kstep, b2 = last ? nB : cB + (size_t)(t + 2) * kstep;
;             const Src a3 = a2 + kstep, b3 = b2 + kstep;
;             if (last && has_next) H(nxt);
;             if constexpr (SP2) {
;             PG8_TRIP_SP2(PG8_WAIT_V(8));
	s_setprio 0
	s_mov_b32 m0, s39
	s_or_b32 s64, s62, 0x80
	ds_read_b128 v[168:171], v162 offset:49152
	ds_read_b128 v[172:175], v162 offset:50176
	ds_read_b128 v[176:179], v162 offset:51200
	ds_read_b128 v[180:183], v162 offset:52224
	ds_read_b128 v[184:187], v162 offset:53248
	ds_read_b128 v[188:191], v162 offset:54272
	ds_read_b128 v[192:195], v162 offset:55296
	ds_read_b128 v[200:203], v162 offset:56320
	buffer_load_dwordx4 v158, s[16:19], s64 offen lds
	s_mov_b32 m0, s40
	s_add_i32 s62, s62, 0xb0080
	buffer_load_dwordx4 v160, s[16:19], s64 offen lds
	s_mov_b32 m0, s43
	s_nop 0
	buffer_load_dwordx4 v158, s[16:19], s62 offen lds
	s_mov_b32 m0, s42
	s_nop 0
	buffer_load_dwordx4 v160, s[16:19], s62 offen lds
	s_waitcnt vmcnt(6)
	s_waitcnt lgkmcnt(0)
	s_setprio 1
	s_barrier
	v_mfma_f32_16x16x32_bf16 v[62:65], v[130:133], v[168:171], v[62:65]
	v_mfma_f32_16x16x32_bf16 v[58:61], v[138:141], v[168:171], v[58:61]
	v_mfma_f32_16x16x32_bf16 v[46:49], v[130:133], v[176:179], v[46:49]
	v_mfma_f32_16x16x32_bf16 v[42:45], v[138:141], v[176:179], v[42:45]
	v_mfma_f32_16x16x32_bf16 v[30:33], v[130:133], v[184:187], v[30:33]
	v_mfma_f32_16x16x32_bf16 v[26:29], v[138:141], v[184:187], v[26:29]
	v_mfma_f32_16x16x32_bf16 v[14:17], v[130:133], v[192:195], v[14:17]
	v_mfma_f32_16x16x32_bf16 v[10:13], v[138:141], v[192:195], v[10:13]
	v_mfma_f32_16x16x32_bf16 v[62:65], v[134:137], v[172:175], v[62:65]
	v_mfma_f32_16x16x32_bf16 v[58:61], v[142:145], v[172:175], v[58:61]
	v_mfma_f32_16x16x32_bf16 v[46:49], v[134:137], v[180:183], v[46:49]
	v_mfma_f32_16x16x32_bf16 v[42:45], v[142:145], v[180:183], v[42:45]
	v_mfma_f32_16x16x32_bf16 v[30:33], v[134:137], v[188:191], v[30:33]
	v_mfma_f32_16x16x32_bf16 v[26:29], v[142:145], v[188:191], v[26:29]
	v_mfma_f32_16x16x32_bf16 v[14:17], v[134:137], v[200:203], v[14:17]
	v_mfma_f32_16x16x32_bf16 v[10:13], v[142:145], v[200:203], v[10:13]
	v_mfma_f32_16x16x32_bf16 v[54:57], v[146:149], v[168:171], v[54:57]
	v_mfma_f32_16x16x32_bf16 v[50:53], v[154:157], v[168:171], v[50:53]
	v_mfma_f32_16x16x32_bf16 v[38:41], v[146:149], v[176:179], v[38:41]
	v_mfma_f32_16x16x32_bf16 v[34:37], v[154:157], v[176:179], v[34:37]
	v_mfma_f32_16x16x32_bf16 v[22:25], v[146:149], v[184:187], v[22:25]
	v_mfma_f32_16x16x32_bf16 v[18:21], v[154:157], v[184:187], v[18:21]
	v_mfma_f32_16x16x32_bf16 v[6:9], v[146:149], v[192:195], v[6:9]
	v_mfma_f32_16x16x32_bf16 v[2:5], v[154:157], v[192:195], v[2:5]
	v_mfma_f32_16x16x32_bf16 v[54:57], v[150:153], v[172:175], v[54:57]
	v_mfma_f32_16x16x32_bf16 v[50:53], v[164:167], v[172:175], v[50:53]
	v_mfma_f32_16x16x32_bf16 v[38:41], v[150:153], v[180:183], v[38:41]
	v_mfma_f32_16x16x32_bf16 v[34:37], v[164:167], v[180:183], v[34:37]
	v_mfma_f32_16x16x32_bf16 v[22:25], v[150:153], v[188:191], v[22:25]
	v_mfma_f32_16x16x32_bf16 v[18:21], v[164:167], v[188:191], v[18:21]
	v_mfma_f32_16x16x32_bf16 v[6:9], v[150:153], v[200:203], v[6:9]
	v_mfma_f32_16x16x32_bf16 v[2:5], v[164:167], v[200:203], v[2:5]
	s_barrier
	s_setprio 0
	s_add_i32 s61, s61, 2
	s_addk_i32 s2, 0x100
	s_addk_i32 s3, 0x100
	s_cmp_gt_u32 s61, 41
	s_cbranch_scc0 .LBB0_1572
	s_mov_b32 m0, s41
	s_nop 0
	buffer_load_dwordx4 v0, s[20:23], s63 offen lds
	s_mov_b32 m0, s33
	s_nop 0
	buffer_load_dwordx4 v159, s[20:23], s63 offen lds
	v_readlane_b32 s2, v251, 45
	v_readlane_b32 s3, v251, 46
	s_and_b64 vcc, exec, s[2:3]
	s_cbranch_vccz .LBB0_1575
	s_barrier

; #define PG8_WAIT_V(n) asm volatile("s_waitcnt vmcnt(" #n ")" ::: "memory")
; template <class Epi, bool ALIGN_EPI, bool SP2, class Hook>
; __device__ __forceinline__ void gemm_phase(LAS unsigned char* lds, const Gemm g, const StaticOrder& S, const Epi& E, Acc& acc, const bool fresh, const Hook& H, const int wave_id) {
;     ...
;             const bool last = (t == nt - 2);
;             const Src a1 = cA + (size_t)(t + 1) * kstep;
;             const Src a2 = last ? nA : cA + (size_t)(t + 2) * kstep, b2 = last ? nB : cB + (size_t)(t + 2) * kstep;
;             const Src a3 = a2 + kstep, b3 = b2 + kstep;
;             if (last && has_next) H(nxt);
;             if constexpr (SP2) {
;             PG8_TRIP_SP2(PG8_WAIT_V(8));
.LBB0_1614:
	s_add_i32 s100, s2, 0xfff40000
	v_add_u32_e32 v0, 0x10000, v172
	ds_read_b128 v[130:133], v0
	ds_read_b128 v[134:137], v0 offset:1024
	ds_read_b128 v[138:141], v0 offset:2048
	ds_read_b128 v[142:145], v0 offset:3072
	v_add_u32_e32 v0, 0x14000, v172
	ds_read_b128 v[146:149], v0
	ds_read_b128 v[150:153], v0 offset:1024
	ds_read_b128 v[154:157], v0 offset:2048
	ds_read_b128 v[158:161], v0 offset:3072
	s_add_i32 s12, s2, 0xfff40080
	s_cmp_eq_u32 s59, 40
	s_cselect_b32 s62, s55, s12
	s_cselect_b32 s13, s31, s77
	s_cselect_b32 s12, s30, s76
	s_cselect_b32 s15, s35, s51
	s_cselect_b32 s14, s34, s50
	s_cselect_b32 s60, s56, s3
	s_cselect_b32 s16, s20, s8
	s_cselect_b32 s17, s21, s9
	s_cselect_b32 s18, s22, s10
	s_cselect_b32 s19, s23, s11
	s_or_b32 s61, s62, 0x80
	s_mov_b32 m0, s45
	ds_read_b128 v[162:165], v173
	ds_read_b128 v[174:177], v173 offset:1024
	ds_read_b128 v[178:181], v173 offset:2048
	ds_read_b128 v[182:185], v173 offset:3072
	ds_read_b128 v[186:189], v173 offset:4096
	ds_read_b128 v[190:193], v173 offset:5120
	ds_read_b128 v[194:197], v173 offset:6144
	ds_read_b128 v[200:203], v173 offset:7168
	s_mov_b32 m0, s41
	s_nop 0
	buffer_load_dwordx4 v168, s[8:11], s100 offen lds
	s_mov_b32 m0, s33
	s_nop 0
	buffer_load_dwordx4 v170, s[8:11], s100 offen lds
	s_mov_b32 m0, s45
	s_nop 0
	buffer_load_dwordx4 v168, s[8:11], s2 offen lds
	s_mov_b32 m0, s46
	s_nop 0
	buffer_load_dwordx4 v170, s[8:11], s2 offen lds
	s_waitcnt vmcnt(8)
	s_waitcnt lgkmcnt(0)
	s_setprio 1
	s_barrier
	v_mfma_f32_16x16x32_bf16 v[126:129], v[130:133], v[162:165], v[126:129]
	v_mfma_f32_16x16x32_bf16 v[122:125], v[138:141], v[162:165], v[122:125]
	v_mfma_f32_16x16x32_bf16 v[110:113], v[130:133], v[178:181], v[110:113]
	v_mfma_f32_16x16x32_bf16 v[106:109], v[138:141], v[178:181], v[106:109]
	v_mfma_f32_16x16x32_bf16 v[94:97], v[130:133], v[186:189], v[94:97]
	v_mfma_f32_16x16x32_bf16 v[90:93], v[138:141], v[186:189], v[90:93]
	v_mfma_f32_16x16x32_bf16 v[78:81], v[130:133], v[194:197], v[78:81]
	v_mfma_f32_16x16x32_bf16 v[74:77], v[138:141], v[194:197], v[74:77]
	v_mfma_f32_16x16x32_bf16 v[126:129], v[134:137], v[174:177], v[126:129]
	v_mfma_f32_16x16x32_bf16 v[122:125], v[142:145], v[174:177], v[122:125]
	v_mfma_f32_16x16x32_bf16 v[110:113], v[134:137], v[182:185], v[110:113]
	v_mfma_f32_16x16x32_bf16 v[106:109], v[142:145], v[182:185], v[106:109]
	v_mfma_f32_16x16x32_bf16 v[94:97], v[134:137], v[190:193], v[94:97]
	v_mfma_f32_16x16x32_bf16 v[90:93], v[142:145], v[190:193], v[90:93]
	v_mfma_f32_16x16x32_bf16 v[78:81], v[134:137], v[200:203], v[78:81]
	v_mfma_f32_16x16x32_bf16 v[74:77], v[142:145], v[200:203], v[74:77]
	v_mfma_f32_16x16x32_bf16 v[118:121], v[146:149], v[162:165], v[118:121]
	v_mfma_f32_16x16x32_bf16 v[114:117], v[154:157], v[162:165], v[114:117]
	v_mfma_f32_16x16x32_bf16 v[102:105], v[146:149], v[178:181], v[102:105]
	v_mfma_f32_16x16x32_bf16 v[98:101], v[154:157], v[178:181], v[98:101]
	v_mfma_f32_16x16x32_bf16 v[86:89], v[146:149], v[186:189], v[86:89]
	v_mfma_f32_16x16x32_bf16 v[82:85], v[154:157], v[186:189], v[82:85]
	v_mfma_f32_16x16x32_bf16 v[70:73], v[146:149], v[194:197], v[70:73]
	v_mfma_f32_16x16x32_bf16 v[66:69], v[154:157], v[194:197], v[66:69]
	v_mfma_f32_16x16x32_bf16 v[118:121], v[150:153], v[174:177], v[118:121]
	v_mfma_f32_16x16x32_bf16 v[114:117], v[158:161], v[174:177], v[114:117]
	v_mfma_f32_16x16x32_bf16 v[102:105], v[150:153], v[182:185], v[102:105]
	v_mfma_f32_16x16x32_bf16 v[98:101], v[158:161], v[182:185], v[98:101]
	v_mfma_f32_16x16x32_bf16 v[86:89], v[150:153], v[190:193], v[86:89]
	v_mfma_f32_16x16x32_bf16 v[82:85], v[158:161], v[190:193], v[82:85]
	v_mfma_f32_16x16x32_bf16 v[70:73], v[150:153], v[200:203], v[70:73]
	v_mfma_f32_16x16x32_bf16 v[66:69], v[158:161], v[200:203], v[66:69]
	s_barrier
	s_setprio 0
	s_mov_b32 m0, s92
	ds_read_b128 v[162:165], v173 offset:16384
	ds_read_b128 v[174:177], v173 offset:17408
	ds_read_b128 v[178:181], v173 offset:18432
	ds_read_b128 v[182:185], v173 offset:19456
	ds_read_b128 v[186:189], v173 offset:20480
	ds_read_b128 v[190:193], v173 offset:21504
	ds_read_b128 v[194:197], v173 offset:22528
	ds_read_b128 v[200:203], v173 offset:23552
	buffer_load_dwordx4 v169, s[12:15], s60 offen lds
	s_mov_b32 m0, s93
	s_add_i32 s63, s60, 0xb0000
	buffer_load_dwordx4 v171, s[12:15], s60 offen lds
	s_mov_b32 m0, s94
	s_nop 0
	buffer_load_dwordx4 v169, s[12:15], s63 offen lds
	s_mov_b32 m0, s95
	s_nop 0
	buffer_load_dwordx4 v171, s[12:15], s63 offen lds
	s_mov_b32 s101, s62
	s_waitcnt vmcnt(6)
	s_waitcnt lgkmcnt(0)
	s_setprio 1
	s_barrier
	v_mfma_f32_16x16x32_bf16 v[62:65], v[130:133], v[162:165], v[62:65]
	v_mfma_f32_16x16x32_bf16 v[58:61], v[138:141], v[162:165], v[58:61]
	v_mfma_f32_16x16x32_bf16 v[46:49], v[130:133], v[178:181], v[46:49]
	v_mfma_f32_16x16x32_bf16 v[42:45], v[138:141], v[178:181], v[42:45]
	v_mfma_f32_16x16x32_bf16 v[30:33], v[130:133], v[186:189], v[30:33]
	v_mfma_f32_16x16x32_bf16 v[26:29], v[138:141], v[186:189], v[26:29]
	v_mfma_f32_16x16x32_bf16 v[14:17], v[130:133], v[194:197], v[14:17]
	v_mfma_f32_16x16x32_bf16 v[10:13], v[138:141], v[194:197], v[10:13]
	v_mfma_f32_16x16x32_bf16 v[62:65], v[134:137], v[174:177], v[62:65]
	v_mfma_f32_16x16x32_bf16 v[58:61], v[142:145], v[174:177], v[58:61]
	v_mfma_f32_16x16x32_bf16 v[46:49], v[134:137], v[182:185], v[46:49]
	v_mfma_f32_16x16x32_bf16 v[42:45], v[142:145], v[182:185], v[42:45]
	v_mfma_f32_16x16x32_bf16 v[30:33], v[134:137], v[190:193], v[30:33]
	v_mfma_f32_16x16x32_bf16 v[26:29], v[142:145], v[190:193], v[26:29]
	v_mfma_f32_16x16x32_bf16 v[14:17], v[134:137], v[200:203], v[14:17]
	v_mfma_f32_16x16x32_bf16 v[10:13], v[142:145], v[200:203], v[10:13]
	v_mfma_f32_16x16x32_bf16 v[54:57], v[146:149], v[162:165], v[54:57]
	v_mfma_f32_16x16x32_bf16 v[50:53], v[154:157], v[162:165], v[50:53]
	v_mfma_f32_16x16x32_bf16 v[38:41], v[146:149], v[178:181], v[38:41]
	v_mfma_f32_16x16x32_bf16 v[34:37], v[154:157], v[178:181], v[34:37]
	v_mfma_f32_16x16x32_bf16 v[22:25], v[146:149], v[186:189], v[22:25]
	v_mfma_f32_16x16x32_bf16 v[18:21], v[154:157], v[186:189], v[18:21]
	v_mfma_f32_16x16x32_bf16 v[6:9], v[146:149], v[194:197], v[6:9]
	v_mfma_f32_16x16x32_bf16 v[2:5], v[154:157], v[194:197], v[2:5]
	v_mfma_f32_16x16x32_bf16 v[54:57], v[150:153], v[174:177], v[54:57]
	v_mfma_f32_16x16x32_bf16 v[50:53], v[158:161], v[174:177], v[50:53]
	v_mfma_f32_16x16x32_bf16 v[38:41], v[150:153], v[182:185], v[38:41]
	v_mfma_f32_16x16x32_bf16 v[34:37], v[158:161], v[182:185], v[34:37]
	v_mfma_f32_16x16x32_bf16 v[22:25], v[150:153], v[190:193], v[22:25]
	v_mfma_f32_16x16x32_bf16 v[18:21], v[158:161], v[190:193], v[18:21]
	v_mfma_f32_16x16x32_bf16 v[6:9], v[150:153], v[200:203], v[6:9]
	v_mfma_f32_16x16x32_bf16 v[2:5], v[158:161], v[200:203], v[2:5]
	s_barrier
	s_setprio 0
	v_add_u32_e32 v0, 0x18000, v172
	ds_read_b128 v[130:133], v0
	ds_read_b128 v[134:137], v0 offset:1024
	ds_read_b128 v[138:141], v0 offset:2048
	ds_read_b128 v[142:145], v0 offset:3072
	v_add_u32_e32 v0, 0x1c000, v172
	ds_read_b128 v[146:149], v0
	ds_read_b128 v[150:153], v0 offset:1024
	ds_read_b128 v[154:157], v0 offset:2048
	ds_read_b128 v[158:161], v0 offset:3072
	s_add_i32 s62, s62, 0xc0000
	s_mov_b32 m0, s37
	ds_read_b128 v[162:165], v173 offset:32768
	ds_read_b128 v[174:177], v173 offset:33792
	ds_read_b128 v[178:181], v173 offset:34816
	ds_read_b128 v[182:185], v173 offset:35840
	ds_read_b128 v[186:189], v173 offset:36864
	ds_read_b128 v[190:193], v173 offset:37888
	ds_read_b128 v[194:197], v173 offset:38912
	ds_read_b128 v[200:203], v173 offset:39936
	s_mov_b32 m0, s44
	s_nop 0
	buffer_load_dwordx4 v168, s[16:19], s101 offen lds
	s_mov_b32 m0, s36
	s_nop 0
	buffer_load_dwordx4 v170, s[16:19], s101 offen lds
	s_mov_b32 m0, s37
	s_nop 0
	buffer_load_dwordx4 v168, s[16:19], s62 offen lds
	s_mov_b32 m0, s38
	s_nop 0
	buffer_load_dwordx4 v170, s[16:19], s62 offen lds
	s_waitcnt vmcnt(8)
	s_waitcnt lgkmcnt(0)
	s_setprio 1
	s_barrier
	v_mfma_f32_16x16x32_bf16 v[126:129], v[130:133], v[162:165], v[126:129]
	v_mfma_f32_16x16x32_bf16 v[122:125], v[138:141], v[162:165], v[122:125]
	v_mfma_f32_16x16x32_bf16 v[110:113], v[130:133], v[178:181], v[110:113]
	v_mfma_f32_16x16x32_bf16 v[106:109], v[138:141], v[178:181], v[106:109]
	v_mfma_f32_16x16x32_bf16 v[94:97], v[130:133], v[186:189], v[94:97]
	v_mfma_f32_16x16x32_bf16 v[90:93], v[138:141], v[186:189], v[90:93]
	v_mfma_f32_16x16x32_bf16 v[78:81], v[130:133], v[194:197], v[78:81]
	v_mfma_f32_16x16x32_bf16 v[74:77], v[138:141], v[194:197], v[74:77]
	v_mfma_f32_16x16x32_bf16 v[126:129], v[134:137], v[174:177], v[126:129]
	v_mfma_f32_16x16x32_bf16 v[122:125], v[142:145], v[174:177], v[122:125]
	v_mfma_f32_16x16x32_bf16 v[110:113], v[134:137], v[182:185], v[110:113]
	v_mfma_f32_16x16x32_bf16 v[106:109], v[142:145], v[182:185], v[106:109]
	v_mfma_f32_16x16x32_bf16 v[94:97], v[134:137], v[190:193], v[94:97]
	v_mfma_f32_16x16x32_bf16 v[90:93], v[142:145], v[190:193], v[90:93]
	v_mfma_f32_16x16x32_bf16 v[78:81], v[134:137], v[200:203], v[78:81]
	v_mfma_f32_16x16x32_bf16 v[74:77], v[142:145], v[200:203], v[74:77]
	v_mfma_f32_16x16x32_bf16 v[118:121], v[146:149], v[162:165], v[118:121]
	v_mfma_f32_16x16x32_bf16 v[114:117], v[154:157], v[162:165], v[114:117]
	v_mfma_f32_16x16x32_bf16 v[102:105], v[146:149], v[178:181], v[102:105]
	v_mfma_f32_16x16x32_bf16 v[98:101], v[154:157], v[178:181], v[98:101]
	v_mfma_f32_16x16x32_bf16 v[86:89], v[146:149], v[186:189], v[86:89]
	v_mfma_f32_16x16x32_bf16 v[82:85], v[154:157], v[186:189], v[82:85]
	v_mfma_f32_16x16x32_bf16 v[70:73], v[146:149], v[194:197], v[70:73]
	v_mfma_f32_16x16x32_bf16 v[66:69], v[154:157], v[194:197], v[66:69]
	v_mfma_f32_16x16x32_bf16 v[118:121], v[150:153], v[174:177], v[118:121]
	v_mfma_f32_16x16x32_bf16 v[114:117], v[158:161], v[174:177], v[114:117]
	v_mfma_f32_16x16x32_bf16 v[102:105], v[150:153], v[182:185], v[102:105]
	v_mfma_f32_16x16x32_bf16 v[98:101], v[158:161], v[182:185], v[98:101]
	v_mfma_f32_16x16x32_bf16 v[86:89], v[150:153], v[190:193], v[86:89]
	v_mfma_f32_16x16x32_bf16 v[82:85], v[158:161], v[190:193], v[82:85]
	v_mfma_f32_16x16x32_bf16 v[70:73], v[150:153], v[200:203], v[70:73]
	v_mfma_f32_16x16x32_bf16 v[66:69], v[158:161], v[200:203], v[66:69]
	s_barrier
; #define PG8_WAIT_V(n) asm volatile("s_waitcnt vmcnt(" #n ")" ::: "memory")
; template <class Epi, bool ALIGN_EPI, bool SP2, class Hook>
; __device__ __forceinline__ void gemm_phase(LAS unsigned char* lds, const Gemm g, const StaticOrder& S, const Epi& E, Acc& acc, const bool fresh, const Hook& H, const int wave_id) {
;     ...
;         for (int t = t0; t < nt; t += 2) {
;             const bool last = (t == nt - 2);
;             const Src a1 = cA + (size_t)(t + 1) * kstep;
;             const Src a2 = last ? nA : cA + (size_t)(t + 2) * kstep, b2 = last ? nB : cB + (size_t)(t + 2) * kstep;
;             const Src a3 = a2 + kstep, b3 = b2 + kstep;
;             if (last && has_next) H(nxt);
;             if constexpr (SP2) {
;             PG8_TRIP_SP2(PG8_WAIT_V(8));
	s_setprio 0
	s_mov_b32 m0, s39
	s_or_b32 s62, s60, 0x80
	ds_read_b128 v[162:165], v173 offset:49152
	ds_read_b128 v[174:177], v173 offset:50176
	ds_read_b128 v[178:181], v173 offset:51200
	ds_read_b128 v[182:185], v173 offset:52224
	ds_read_b128 v[186:189], v173 offset:53248
	ds_read_b128 v[190:193], v173 offset:54272
	ds_read_b128 v[194:197], v173 offset:55296
	ds_read_b128 v[200:203], v173 offset:56320
	buffer_load_dwordx4 v169, s[12:15], s62 offen lds
	s_mov_b32 m0, s40
	s_add_i32 s60, s60, 0xb0080
	buffer_load_dwordx4 v171, s[12:15], s62 offen lds
	s_mov_b32 m0, s43
	s_nop 0
	buffer_load_dwordx4 v169, s[12:15], s60 offen lds
	s_mov_b32 m0, s42
	s_nop 0
	buffer_load_dwordx4 v171, s[12:15], s60 offen lds
	s_waitcnt vmcnt(6)
	s_waitcnt lgkmcnt(0)
	s_setprio 1
	s_barrier
	v_mfma_f32_16x16x32_bf16 v[62:65], v[130:133], v[162:165], v[62:65]
	v_mfma_f32_16x16x32_bf16 v[58:61], v[138:141], v[162:165], v[58:61]
	v_mfma_f32_16x16x32_bf16 v[46:49], v[130:133], v[178:181], v[46:49]
	v_mfma_f32_16x16x32_bf16 v[42:45], v[138:141], v[178:181], v[42:45]
	v_mfma_f32_16x16x32_bf16 v[30:33], v[130:133], v[186:189], v[30:33]
	v_mfma_f32_16x16x32_bf16 v[26:29], v[138:141], v[186:189], v[26:29]
	v_mfma_f32_16x16x32_bf16 v[14:17], v[130:133], v[194:197], v[14:17]
	v_mfma_f32_16x16x32_bf16 v[10:13], v[138:141], v[194:197], v[10:13]
	v_mfma_f32_16x16x32_bf16 v[62:65], v[134:137], v[174:177], v[62:65]
	v_mfma_f32_16x16x32_bf16 v[58:61], v[142:145], v[174:177], v[58:61]
	v_mfma_f32_16x16x32_bf16 v[46:49], v[134:137], v[182:185], v[46:49]
	v_mfma_f32_16x16x32_bf16 v[42:45], v[142:145], v[182:185], v[42:45]
	v_mfma_f32_16x16x32_bf16 v[30:33], v[134:137], v[190:193], v[30:33]
	v_mfma_f32_16x16x32_bf16 v[26:29], v[142:145], v[190:193], v[26:29]
	v_mfma_f32_16x16x32_bf16 v[14:17], v[134:137], v[200:203], v[14:17]
	v_mfma_f32_16x16x32_bf16 v[10:13], v[142:145], v[200:203], v[10:13]
	v_mfma_f32_16x16x32_bf16 v[54:57], v[146:149], v[162:165], v[54:57]
	v_mfma_f32_16x16x32_bf16 v[50:53], v[154:157], v[162:165], v[50:53]
	v_mfma_f32_16x16x32_bf16 v[38:41], v[146:149], v[178:181], v[38:41]
	v_mfma_f32_16x16x32_bf16 v[34:37], v[154:157], v[178:181], v[34:37]
	v_mfma_f32_16x16x32_bf16 v[22:25], v[146:149], v[186:189], v[22:25]
	v_mfma_f32_16x16x32_bf16 v[18:21], v[154:157], v[186:189], v[18:21]
	v_mfma_f32_16x16x32_bf16 v[6:9], v[146:149], v[194:197], v[6:9]
	v_mfma_f32_16x16x32_bf16 v[2:5], v[154:157], v[194:197], v[2:5]
	v_mfma_f32_16x16x32_bf16 v[54:57], v[150:153], v[174:177], v[54:57]
	v_mfma_f32_16x16x32_bf16 v[50:53], v[158:161], v[174:177], v[50:53]
	v_mfma_f32_16x16x32_bf16 v[38:41], v[150:153], v[182:185], v[38:41]
	v_mfma_f32_16x16x32_bf16 v[34:37], v[158:161], v[182:185], v[34:37]
	v_mfma_f32_16x16x32_bf16 v[22:25], v[150:153], v[190:193], v[22:25]
	v_mfma_f32_16x16x32_bf16 v[18:21], v[158:161], v[190:193], v[18:21]
	v_mfma_f32_16x16x32_bf16 v[6:9], v[150:153], v[200:203], v[6:9]
	v_mfma_f32_16x16x32_bf16 v[2:5], v[158:161], v[200:203], v[2:5]
	s_barrier
	s_setprio 0
	s_add_i32 s59, s59, 2
	s_addk_i32 s2, 0x100
	s_addk_i32 s3, 0x100
	s_cmp_gt_u32 s59, 41
	s_cbranch_scc0 .LBB0_1614
	s_mov_b32 m0, s41
	s_nop 0
	buffer_load_dwordx4 v168, s[16:19], s61 offen lds
	s_mov_b32 m0, s33
	s_nop 0
	buffer_load_dwordx4 v170, s[16:19], s61 offen lds
	v_readlane_b32 s2, v251, 45
	v_readlane_b32 s3, v251, 46
	s_and_b64 vcc, exec, s[2:3]
	s_cbranch_vccz .LBB0_1617
	s_barrier
